# speedup vs baseline: 1.3303x; 1.0023x over previous
; #define LAS __attribute__((address_space(3)))
; __device__ __forceinline__ float logsigmoid_fast(float x) { return fminf(x, 0.f) - __logf(1.0f + __expf(-fabsf(x))); }
; template <int KIND, int MODE>
; __device__ __forceinline__ void scan_unit(Frame& F, int layer, int h, int vhalf, int grp) {
;     ...
;         for (int i = 0; i < 2; ++i) { const int e = tid + 512 * i; *(LAS u32x4*)(VS + (e >> 4) * VST + (e & 15) * 8) = pv[i]; }
;         if (KIND == 0) {
; #pragma unroll
;             for (int i = 0; i < 2; ++i) { const int c = tid + 512 * i, t = c >> 4, dc = (c & 15) * 8; const bf16_t* rp = proj + (size_t)(tb + t) * NP + h * 128 + dc;
;                 if (MODE == 1) *(LAS u32x4*)(QS + t * QST + dc) = pq[i];
;                 *(LAS u32x4*)(KS + t * QST + dc) = pk[i]; }
;             X[tid] = pl0; X[tid + 512] = pl1;
;             __syncthreads();
;             float bc[RPT]; float run = 0.f;
; #pragma unroll
;             for (int i = 0; i < RPT; ++i) { const LAS f32x4* lr = (const LAS f32x4*)(X + (tq * RPT + i) * 16); float z = bl;
; #pragma unroll
;                 for (int r = 0; r < 4; ++r) { const f32x4 l4 = lr[r]; z += l4[0] * wl[4 * r] + l4[1] * wl[4 * r + 1] + l4[2] * wl[4 * r + 2] + l4[3] * wl[4 * r + 3]; }
;                 run += logsigmoid_fast(z) * (1.0f / 16.0f); bc[i] = run; }
.LBB0_424:
	v_add_u32_e32 v50, v92, v97
	ds_write_b128 v50, v[2:5]
	v_add_u32_e32 v50, v92, v98
	ds_write_b128 v50, v[6:9]
	v_add_u32_e32 v50, v0, v97
	ds_write_b128 v50, v[10:13] offset:33792
	v_add_u32_e32 v50, v0, v98
	ds_write_b128 v50, v[14:17] offset:33792
	ds_write2st64_b32 v93, v61, v60 offset1:8
	s_waitcnt lgkmcnt(0)
	s_barrier
	ds_read_b128 v[180:183], v94
	ds_read_b128 v[184:187], v94 offset:16
	ds_read_b128 v[188:191], v94 offset:32
	ds_read_b128 v[192:195], v94 offset:48
	ds_read_b128 v[196:199], v94 offset:64
	ds_read_b128 v[200:203], v94 offset:80
	ds_read_b128 v[204:207], v94 offset:96
	ds_read_b128 v[208:211], v94 offset:112
	s_waitcnt lgkmcnt(4)
	v_mul_f32_e32 v212, v76, v181
	v_fmac_f32_e32 v212, v75, v180
	v_fmac_f32_e32 v212, v77, v182
	v_fmac_f32_e32 v212, v78, v183
	v_add_f32_e32 v213, v91, v212
	v_mul_f32_e32 v212, v80, v185
	v_fmac_f32_e32 v212, v79, v184
	v_fmac_f32_e32 v212, v81, v186
	v_fmac_f32_e32 v212, v82, v187
	v_add_f32_e32 v213, v213, v212
	v_mul_f32_e32 v212, v84, v189
	v_fmac_f32_e32 v212, v83, v188
	v_fmac_f32_e32 v212, v85, v190
	v_fmac_f32_e32 v212, v86, v191
	v_add_f32_e32 v213, v213, v212
	v_mul_f32_e32 v212, v88, v193
	v_fmac_f32_e32 v212, v87, v192
	v_fmac_f32_e32 v212, v89, v194
	v_fmac_f32_e32 v212, v90, v195
	v_add_f32_e32 v213, v213, v212
	v_min_f32_e32 v214, 0, v213
	v_mul_f32_e64 v213, |v213|, s65
	v_exp_f32_e32 v213, v213
	s_nop 0
	v_add_f32_e32 v213, 1.0, v213
	v_cmp_gt_f32_e64 s[16:17], s88, v213
	s_nop 1
	v_cndmask_b32_e64 v212, 0, 32, s[16:17]
	v_ldexp_f32 v213, v213, v212
	v_log_f32_e32 v213, v213
	s_nop 0
	v_mul_f32_e32 v212, 0x3f317217, v213
	v_fma_f32 v212, v213, s75, -v212
	v_fmac_f32_e32 v212, 0x3377d1cf, v213
	v_fmac_f32_e32 v212, 0x3f317217, v213
	v_cmp_lt_f32_e64 s[18:19], |v213|, s51
	s_nop 1
	v_cndmask_b32_e64 v213, v213, v212, s[18:19]
	v_cndmask_b32_e64 v212, 0, v233, s[16:17]
	v_sub_f32_e32 v213, v213, v212
	v_sub_f32_e32 v213, v214, v213
	v_fma_f32 v50, v213, s64, 0
	ds_read_b128 v[180:183], v94 offset:128
	ds_read_b128 v[184:187], v94 offset:144
	ds_read_b128 v[188:191], v94 offset:160
	ds_read_b128 v[192:195], v94 offset:176
	s_waitcnt lgkmcnt(4)
	v_mul_f32_e32 v212, v76, v197
	v_fmac_f32_e32 v212, v75, v196
	v_fmac_f32_e32 v212, v77, v198
	v_fmac_f32_e32 v212, v78, v199
	v_add_f32_e32 v213, v91, v212
	v_mul_f32_e32 v212, v80, v201
	v_fmac_f32_e32 v212, v79, v200
	v_fmac_f32_e32 v212, v81, v202
	v_fmac_f32_e32 v212, v82, v203
	v_add_f32_e32 v213, v213, v212
	v_mul_f32_e32 v212, v84, v205
	v_fmac_f32_e32 v212, v83, v204
	v_fmac_f32_e32 v212, v85, v206
	v_fmac_f32_e32 v212, v86, v207
	v_add_f32_e32 v213, v213, v212
	v_mul_f32_e32 v212, v88, v209
	v_fmac_f32_e32 v212, v87, v208
	v_fmac_f32_e32 v212, v89, v210
	v_fmac_f32_e32 v212, v90, v211
	v_add_f32_e32 v213, v213, v212
	v_min_f32_e32 v214, 0, v213
	v_mul_f32_e64 v213, |v213|, s65
	v_exp_f32_e32 v213, v213
	s_nop 0
	v_add_f32_e32 v213, 1.0, v213
	v_cmp_gt_f32_e64 s[16:17], s88, v213
	s_nop 1
	v_cndmask_b32_e64 v212, 0, 32, s[16:17]
	v_ldexp_f32 v213, v213, v212
	v_log_f32_e32 v213, v213
	s_nop 0
	v_mul_f32_e32 v212, 0x3f317217, v213
	v_fma_f32 v212, v213, s75, -v212
	v_fmac_f32_e32 v212, 0x3377d1cf, v213
	v_fmac_f32_e32 v212, 0x3f317217, v213
	v_cmp_lt_f32_e64 s[18:19], |v213|, s51
	s_nop 1
	v_cndmask_b32_e64 v213, v213, v212, s[18:19]
	v_cndmask_b32_e64 v212, 0, v233, s[16:17]
	v_sub_f32_e32 v213, v213, v212
	v_sub_f32_e32 v213, v214, v213
	v_fmamk_f32 v51, v213, 0x3d800000, v50
	ds_read_b128 v[196:199], v94 offset:192
	ds_read_b128 v[200:203], v94 offset:208
	ds_read_b128 v[204:207], v94 offset:224
	ds_read_b128 v[208:211], v94 offset:240
	s_waitcnt lgkmcnt(4)
	v_mul_f32_e32 v212, v76, v181
	v_fmac_f32_e32 v212, v75, v180
	v_fmac_f32_e32 v212, v77, v182
	v_fmac_f32_e32 v212, v78, v183
	v_add_f32_e32 v213, v91, v212
	v_mul_f32_e32 v212, v80, v185
	v_fmac_f32_e32 v212, v79, v184
	v_fmac_f32_e32 v212, v81, v186
	v_fmac_f32_e32 v212, v82, v187
	v_add_f32_e32 v213, v213, v212
	v_mul_f32_e32 v212, v84, v189
	v_fmac_f32_e32 v212, v83, v188
	v_fmac_f32_e32 v212, v85, v190
	v_fmac_f32_e32 v212, v86, v191
	v_add_f32_e32 v213, v213, v212
	v_mul_f32_e32 v212, v88, v193
	v_fmac_f32_e32 v212, v87, v192
	v_fmac_f32_e32 v212, v89, v194
	v_fmac_f32_e32 v212, v90, v195
	v_add_f32_e32 v213, v213, v212
	v_min_f32_e32 v214, 0, v213
	v_mul_f32_e64 v213, |v213|, s65
	v_exp_f32_e32 v213, v213
	s_nop 0
	v_add_f32_e32 v213, 1.0, v213
	v_cmp_gt_f32_e64 s[16:17], s88, v213
	s_nop 1
	v_cndmask_b32_e64 v212, 0, 32, s[16:17]
	v_ldexp_f32 v213, v213, v212
	v_log_f32_e32 v213, v213
	s_nop 0
	v_mul_f32_e32 v212, 0x3f317217, v213
	v_fma_f32 v212, v213, s75, -v212
	v_fmac_f32_e32 v212, 0x3377d1cf, v213
	v_fmac_f32_e32 v212, 0x3f317217, v213
	v_cmp_lt_f32_e64 s[18:19], |v213|, s51
	s_nop 1
	v_cndmask_b32_e64 v213, v213, v212, s[18:19]
	v_cndmask_b32_e64 v212, 0, v233, s[16:17]
	v_sub_f32_e32 v213, v213, v212
	v_sub_f32_e32 v213, v214, v213
	v_fmamk_f32 v52, v213, 0x3d800000, v51
	ds_read_b128 v[180:183], v94 offset:256
	ds_read_b128 v[184:187], v94 offset:272
	ds_read_b128 v[188:191], v94 offset:288
	ds_read_b128 v[192:195], v94 offset:304
	s_waitcnt lgkmcnt(4)
; #define LAS __attribute__((address_space(3)))
; __device__ __forceinline__ float logsigmoid_fast(float x) { return fminf(x, 0.f) - __logf(1.0f + __expf(-fabsf(x))); }
; template <int KIND, int MODE>
; __device__ __forceinline__ void scan_unit(Frame& F, int layer, int h, int vhalf, int grp) {
;     ...
;             float bc[RPT]; float run = 0.f;
; #pragma unroll
;             for (int i = 0; i < RPT; ++i) { const LAS f32x4* lr = (const LAS f32x4*)(X + (tq * RPT + i) * 16); float z = bl;
; #pragma unroll
;                 for (int r = 0; r < 4; ++r) { const f32x4 l4 = lr[r]; z += l4[0] * wl[4 * r] + l4[1] * wl[4 * r + 1] + l4[2] * wl[4 * r + 2] + l4[3] * wl[4 * r + 3]; }
;                 run += logsigmoid_fast(z) * (1.0f / 16.0f); bc[i] = run; }
	v_mul_f32_e32 v212, v76, v197
	v_fmac_f32_e32 v212, v75, v196
	v_fmac_f32_e32 v212, v77, v198
	v_fmac_f32_e32 v212, v78, v199
	v_add_f32_e32 v213, v91, v212
	v_mul_f32_e32 v212, v80, v201
	v_fmac_f32_e32 v212, v79, v200
	v_fmac_f32_e32 v212, v81, v202
	v_fmac_f32_e32 v212, v82, v203
	v_add_f32_e32 v213, v213, v212
	v_mul_f32_e32 v212, v84, v205
	v_fmac_f32_e32 v212, v83, v204
	v_fmac_f32_e32 v212, v85, v206
	v_fmac_f32_e32 v212, v86, v207
	v_add_f32_e32 v213, v213, v212
	v_mul_f32_e32 v212, v88, v209
	v_fmac_f32_e32 v212, v87, v208
	v_fmac_f32_e32 v212, v89, v210
	v_fmac_f32_e32 v212, v90, v211
	v_add_f32_e32 v213, v213, v212
	v_min_f32_e32 v214, 0, v213
	v_mul_f32_e64 v213, |v213|, s65
	v_exp_f32_e32 v213, v213
	s_nop 0
	v_add_f32_e32 v213, 1.0, v213
	v_cmp_gt_f32_e64 s[16:17], s88, v213
	s_nop 1
	v_cndmask_b32_e64 v212, 0, 32, s[16:17]
	v_ldexp_f32 v213, v213, v212
	v_log_f32_e32 v213, v213
	s_nop 0
	v_mul_f32_e32 v212, 0x3f317217, v213
	v_fma_f32 v212, v213, s75, -v212
	v_fmac_f32_e32 v212, 0x3377d1cf, v213
	v_fmac_f32_e32 v212, 0x3f317217, v213
	v_cmp_lt_f32_e64 s[18:19], |v213|, s51
	s_nop 1
	v_cndmask_b32_e64 v213, v213, v212, s[18:19]
	v_cndmask_b32_e64 v212, 0, v233, s[16:17]
	v_sub_f32_e32 v213, v213, v212
	v_sub_f32_e32 v213, v214, v213
	v_fmamk_f32 v53, v213, 0x3d800000, v52
	ds_read_b128 v[196:199], v94 offset:320
	ds_read_b128 v[200:203], v94 offset:336
	ds_read_b128 v[204:207], v94 offset:352
	ds_read_b128 v[208:211], v94 offset:368
	s_waitcnt lgkmcnt(4)
	v_mul_f32_e32 v212, v76, v181
	v_fmac_f32_e32 v212, v75, v180
	v_fmac_f32_e32 v212, v77, v182
	v_fmac_f32_e32 v212, v78, v183
	v_add_f32_e32 v213, v91, v212
	v_mul_f32_e32 v212, v80, v185
	v_fmac_f32_e32 v212, v79, v184
	v_fmac_f32_e32 v212, v81, v186
	v_fmac_f32_e32 v212, v82, v187
	v_add_f32_e32 v213, v213, v212
	v_mul_f32_e32 v212, v84, v189
	v_fmac_f32_e32 v212, v83, v188
	v_fmac_f32_e32 v212, v85, v190
	v_fmac_f32_e32 v212, v86, v191
	v_add_f32_e32 v213, v213, v212
	v_mul_f32_e32 v212, v88, v193
	v_fmac_f32_e32 v212, v87, v192
	v_fmac_f32_e32 v212, v89, v194
	v_fmac_f32_e32 v212, v90, v195
	v_add_f32_e32 v213, v213, v212
	v_min_f32_e32 v214, 0, v213
	v_mul_f32_e64 v213, |v213|, s65
	v_exp_f32_e32 v213, v213
	s_nop 0
	v_add_f32_e32 v213, 1.0, v213
	v_cmp_gt_f32_e64 s[16:17], s88, v213
	s_nop 1
	v_cndmask_b32_e64 v212, 0, 32, s[16:17]
	v_ldexp_f32 v213, v213, v212
	v_log_f32_e32 v213, v213
	s_nop 0
	v_mul_f32_e32 v212, 0x3f317217, v213
	v_fma_f32 v212, v213, s75, -v212
	v_fmac_f32_e32 v212, 0x3377d1cf, v213
	v_fmac_f32_e32 v212, 0x3f317217, v213
	v_cmp_lt_f32_e64 s[18:19], |v213|, s51
	s_nop 1
	v_cndmask_b32_e64 v213, v213, v212, s[18:19]
	v_cndmask_b32_e64 v212, 0, v233, s[16:17]
	v_sub_f32_e32 v213, v213, v212
	v_sub_f32_e32 v213, v214, v213
	v_fmamk_f32 v54, v213, 0x3d800000, v53
	ds_read_b128 v[180:183], v94 offset:384
	ds_read_b128 v[184:187], v94 offset:400
	ds_read_b128 v[188:191], v94 offset:416
	ds_read_b128 v[192:195], v94 offset:432
	s_waitcnt lgkmcnt(4)
	v_mul_f32_e32 v212, v76, v197
	v_fmac_f32_e32 v212, v75, v196
	v_fmac_f32_e32 v212, v77, v198
	v_fmac_f32_e32 v212, v78, v199
	v_add_f32_e32 v213, v91, v212
	v_mul_f32_e32 v212, v80, v201
	v_fmac_f32_e32 v212, v79, v200
	v_fmac_f32_e32 v212, v81, v202
	v_fmac_f32_e32 v212, v82, v203
	v_add_f32_e32 v213, v213, v212
	v_mul_f32_e32 v212, v84, v205
	v_fmac_f32_e32 v212, v83, v204
	v_fmac_f32_e32 v212, v85, v206
	v_fmac_f32_e32 v212, v86, v207
	v_add_f32_e32 v213, v213, v212
	v_mul_f32_e32 v212, v88, v209
	v_fmac_f32_e32 v212, v87, v208
	v_fmac_f32_e32 v212, v89, v210
	v_fmac_f32_e32 v212, v90, v211
	v_add_f32_e32 v213, v213, v212
	v_min_f32_e32 v214, 0, v213
	v_mul_f32_e64 v213, |v213|, s65
	v_exp_f32_e32 v213, v213
	s_nop 0
	v_add_f32_e32 v213, 1.0, v213
	v_cmp_gt_f32_e64 s[16:17], s88, v213
	s_nop 1
	v_cndmask_b32_e64 v212, 0, 32, s[16:17]
	v_ldexp_f32 v213, v213, v212
	v_log_f32_e32 v213, v213
	s_nop 0
	v_mul_f32_e32 v212, 0x3f317217, v213
	v_fma_f32 v212, v213, s75, -v212
	v_fmac_f32_e32 v212, 0x3377d1cf, v213
	v_fmac_f32_e32 v212, 0x3f317217, v213
	v_cmp_lt_f32_e64 s[18:19], |v213|, s51
	s_nop 1
	v_cndmask_b32_e64 v213, v213, v212, s[18:19]
	v_cndmask_b32_e64 v212, 0, v233, s[16:17]
	v_sub_f32_e32 v213, v213, v212
	v_sub_f32_e32 v213, v214, v213
	v_fmamk_f32 v55, v213, 0x3d800000, v54
	ds_read_b128 v[196:199], v94 offset:448
	ds_read_b128 v[200:203], v94 offset:464
	ds_read_b128 v[204:207], v94 offset:480
	ds_read_b128 v[208:211], v94 offset:496
	s_waitcnt lgkmcnt(4)
	v_mul_f32_e32 v212, v76, v181
	v_fmac_f32_e32 v212, v75, v180
	v_fmac_f32_e32 v212, v77, v182
	v_fmac_f32_e32 v212, v78, v183
	v_add_f32_e32 v213, v91, v212
	v_mul_f32_e32 v212, v80, v185
	v_fmac_f32_e32 v212, v79, v184
	v_fmac_f32_e32 v212, v81, v186
	v_fmac_f32_e32 v212, v82, v187
	v_add_f32_e32 v213, v213, v212
	v_mul_f32_e32 v212, v84, v189
	v_fmac_f32_e32 v212, v83, v188
	v_fmac_f32_e32 v212, v85, v190
	v_fmac_f32_e32 v212, v86, v191
	v_add_f32_e32 v213, v213, v212
	v_mul_f32_e32 v212, v88, v193
	v_fmac_f32_e32 v212, v87, v192
	v_fmac_f32_e32 v212, v89, v194
	v_fmac_f32_e32 v212, v90, v195
	v_add_f32_e32 v213, v213, v212
	v_min_f32_e32 v214, 0, v213
	v_mul_f32_e64 v213, |v213|, s65
	v_exp_f32_e32 v213, v213
	s_nop 0
	v_add_f32_e32 v213, 1.0, v213
	v_cmp_gt_f32_e64 s[16:17], s88, v213
	s_nop 1
	v_cndmask_b32_e64 v212, 0, 32, s[16:17]
	v_ldexp_f32 v213, v213, v212
	v_log_f32_e32 v213, v213
	s_nop 0
	v_mul_f32_e32 v212, 0x3f317217, v213
	v_fma_f32 v212, v213, s75, -v212
	v_fmac_f32_e32 v212, 0x3377d1cf, v213
	v_fmac_f32_e32 v212, 0x3f317217, v213
	v_cmp_lt_f32_e64 s[18:19], |v213|, s51
	s_nop 1
	v_cndmask_b32_e64 v213, v213, v212, s[18:19]
	v_cndmask_b32_e64 v212, 0, v233, s[16:17]
	v_sub_f32_e32 v213, v213, v212
	v_sub_f32_e32 v213, v214, v213
	v_fmamk_f32 v56, v213, 0x3d800000, v55
	ds_read_b128 v[180:183], v94 offset:512
	ds_read_b128 v[184:187], v94 offset:528
	ds_read_b128 v[188:191], v94 offset:544
	ds_read_b128 v[192:195], v94 offset:560
	s_waitcnt lgkmcnt(4)
; #define LAS __attribute__((address_space(3)))
; __device__ __forceinline__ float logsigmoid_fast(float x) { return fminf(x, 0.f) - __logf(1.0f + __expf(-fabsf(x))); }
; template <int KIND, int MODE>
; __device__ __forceinline__ void scan_unit(Frame& F, int layer, int h, int vhalf, int grp) {
;     ...
;             float bc[RPT]; float run = 0.f;
; #pragma unroll
;             for (int i = 0; i < RPT; ++i) { const LAS f32x4* lr = (const LAS f32x4*)(X + (tq * RPT + i) * 16); float z = bl;
; #pragma unroll
;                 for (int r = 0; r < 4; ++r) { const f32x4 l4 = lr[r]; z += l4[0] * wl[4 * r] + l4[1] * wl[4 * r + 1] + l4[2] * wl[4 * r + 2] + l4[3] * wl[4 * r + 3]; }
;                 run += logsigmoid_fast(z) * (1.0f / 16.0f); bc[i] = run; }
	v_mul_f32_e32 v212, v76, v197
	v_fmac_f32_e32 v212, v75, v196
	v_fmac_f32_e32 v212, v77, v198
	v_fmac_f32_e32 v212, v78, v199
	v_add_f32_e32 v213, v91, v212
	v_mul_f32_e32 v212, v80, v201
	v_fmac_f32_e32 v212, v79, v200
	v_fmac_f32_e32 v212, v81, v202
	v_fmac_f32_e32 v212, v82, v203
	v_add_f32_e32 v213, v213, v212
	v_mul_f32_e32 v212, v84, v205
	v_fmac_f32_e32 v212, v83, v204
	v_fmac_f32_e32 v212, v85, v206
	v_fmac_f32_e32 v212, v86, v207
	v_add_f32_e32 v213, v213, v212
	v_mul_f32_e32 v212, v88, v209
	v_fmac_f32_e32 v212, v87, v208
	v_fmac_f32_e32 v212, v89, v210
	v_fmac_f32_e32 v212, v90, v211
	v_add_f32_e32 v213, v213, v212
	v_min_f32_e32 v214, 0, v213
	v_mul_f32_e64 v213, |v213|, s65
	v_exp_f32_e32 v213, v213
	s_nop 0
	v_add_f32_e32 v213, 1.0, v213
	v_cmp_gt_f32_e64 s[16:17], s88, v213
	s_nop 1
	v_cndmask_b32_e64 v212, 0, 32, s[16:17]
	v_ldexp_f32 v213, v213, v212
	v_log_f32_e32 v213, v213
	s_nop 0
	v_mul_f32_e32 v212, 0x3f317217, v213
	v_fma_f32 v212, v213, s75, -v212
	v_fmac_f32_e32 v212, 0x3377d1cf, v213
	v_fmac_f32_e32 v212, 0x3f317217, v213
	v_cmp_lt_f32_e64 s[18:19], |v213|, s51
	s_nop 1
	v_cndmask_b32_e64 v213, v213, v212, s[18:19]
	v_cndmask_b32_e64 v212, 0, v233, s[16:17]
	v_sub_f32_e32 v213, v213, v212
	v_sub_f32_e32 v213, v214, v213
	v_fmamk_f32 v124, v213, 0x3d800000, v56
	ds_read_b128 v[196:199], v94 offset:576
	ds_read_b128 v[200:203], v94 offset:592
	ds_read_b128 v[204:207], v94 offset:608
	ds_read_b128 v[208:211], v94 offset:624
	s_waitcnt lgkmcnt(4)
	v_mul_f32_e32 v212, v76, v181
	v_fmac_f32_e32 v212, v75, v180
	v_fmac_f32_e32 v212, v77, v182
	v_fmac_f32_e32 v212, v78, v183
	v_add_f32_e32 v213, v91, v212
	v_mul_f32_e32 v212, v80, v185
	v_fmac_f32_e32 v212, v79, v184
	v_fmac_f32_e32 v212, v81, v186
	v_fmac_f32_e32 v212, v82, v187
	v_add_f32_e32 v213, v213, v212
	v_mul_f32_e32 v212, v84, v189
	v_fmac_f32_e32 v212, v83, v188
	v_fmac_f32_e32 v212, v85, v190
	v_fmac_f32_e32 v212, v86, v191
	v_add_f32_e32 v213, v213, v212
	v_mul_f32_e32 v212, v88, v193
	v_fmac_f32_e32 v212, v87, v192
	v_fmac_f32_e32 v212, v89, v194
	v_fmac_f32_e32 v212, v90, v195
	v_add_f32_e32 v213, v213, v212
	v_min_f32_e32 v214, 0, v213
	v_mul_f32_e64 v213, |v213|, s65
	v_exp_f32_e32 v213, v213
	s_nop 0
	v_add_f32_e32 v213, 1.0, v213
	v_cmp_gt_f32_e64 s[16:17], s88, v213
	s_nop 1
	v_cndmask_b32_e64 v212, 0, 32, s[16:17]
	v_ldexp_f32 v213, v213, v212
	v_log_f32_e32 v213, v213
	s_nop 0
	v_mul_f32_e32 v212, 0x3f317217, v213
	v_fma_f32 v212, v213, s75, -v212
	v_fmac_f32_e32 v212, 0x3377d1cf, v213
	v_fmac_f32_e32 v212, 0x3f317217, v213
	v_cmp_lt_f32_e64 s[18:19], |v213|, s51
	s_nop 1
	v_cndmask_b32_e64 v213, v213, v212, s[18:19]
	v_cndmask_b32_e64 v212, 0, v233, s[16:17]
	v_sub_f32_e32 v213, v213, v212
	v_sub_f32_e32 v213, v214, v213
	v_fmamk_f32 v57, v213, 0x3d800000, v124
	ds_read_b128 v[180:183], v94 offset:640
	ds_read_b128 v[184:187], v94 offset:656
	ds_read_b128 v[188:191], v94 offset:672
	ds_read_b128 v[192:195], v94 offset:688
	s_waitcnt lgkmcnt(4)
	v_mul_f32_e32 v212, v76, v197
	v_fmac_f32_e32 v212, v75, v196
	v_fmac_f32_e32 v212, v77, v198
	v_fmac_f32_e32 v212, v78, v199
	v_add_f32_e32 v213, v91, v212
	v_mul_f32_e32 v212, v80, v201
	v_fmac_f32_e32 v212, v79, v200
	v_fmac_f32_e32 v212, v81, v202
	v_fmac_f32_e32 v212, v82, v203
	v_add_f32_e32 v213, v213, v212
	v_mul_f32_e32 v212, v84, v205
	v_fmac_f32_e32 v212, v83, v204
	v_fmac_f32_e32 v212, v85, v206
	v_fmac_f32_e32 v212, v86, v207
	v_add_f32_e32 v213, v213, v212
	v_mul_f32_e32 v212, v88, v209
	v_fmac_f32_e32 v212, v87, v208
	v_fmac_f32_e32 v212, v89, v210
	v_fmac_f32_e32 v212, v90, v211
	v_add_f32_e32 v213, v213, v212
	v_min_f32_e32 v214, 0, v213
	v_mul_f32_e64 v213, |v213|, s65
	v_exp_f32_e32 v213, v213
	s_nop 0
	v_add_f32_e32 v213, 1.0, v213
	v_cmp_gt_f32_e64 s[16:17], s88, v213
	s_nop 1
	v_cndmask_b32_e64 v212, 0, 32, s[16:17]
	v_ldexp_f32 v213, v213, v212
	v_log_f32_e32 v213, v213
	s_nop 0
	v_mul_f32_e32 v212, 0x3f317217, v213
	v_fma_f32 v212, v213, s75, -v212
	v_fmac_f32_e32 v212, 0x3377d1cf, v213
	v_fmac_f32_e32 v212, 0x3f317217, v213
	v_cmp_lt_f32_e64 s[18:19], |v213|, s51
	s_nop 1
	v_cndmask_b32_e64 v213, v213, v212, s[18:19]
	v_cndmask_b32_e64 v212, 0, v233, s[16:17]
	v_sub_f32_e32 v213, v213, v212
	v_sub_f32_e32 v213, v214, v213
	v_fmamk_f32 v125, v213, 0x3d800000, v57
	ds_read_b128 v[196:199], v94 offset:704
	ds_read_b128 v[200:203], v94 offset:720
	ds_read_b128 v[204:207], v94 offset:736
	ds_read_b128 v[208:211], v94 offset:752
	s_waitcnt lgkmcnt(4)
	v_mul_f32_e32 v212, v76, v181
	v_fmac_f32_e32 v212, v75, v180
	v_fmac_f32_e32 v212, v77, v182
	v_fmac_f32_e32 v212, v78, v183
	v_add_f32_e32 v213, v91, v212
	v_mul_f32_e32 v212, v80, v185
	v_fmac_f32_e32 v212, v79, v184
	v_fmac_f32_e32 v212, v81, v186
	v_fmac_f32_e32 v212, v82, v187
	v_add_f32_e32 v213, v213, v212
	v_mul_f32_e32 v212, v84, v189
	v_fmac_f32_e32 v212, v83, v188
	v_fmac_f32_e32 v212, v85, v190
	v_fmac_f32_e32 v212, v86, v191
	v_add_f32_e32 v213, v213, v212
	v_mul_f32_e32 v212, v88, v193
	v_fmac_f32_e32 v212, v87, v192
	v_fmac_f32_e32 v212, v89, v194
	v_fmac_f32_e32 v212, v90, v195
	v_add_f32_e32 v213, v213, v212
	v_min_f32_e32 v214, 0, v213
	v_mul_f32_e64 v213, |v213|, s65
	v_exp_f32_e32 v213, v213
	s_nop 0
	v_add_f32_e32 v213, 1.0, v213
	v_cmp_gt_f32_e64 s[16:17], s88, v213
	s_nop 1
	v_cndmask_b32_e64 v212, 0, 32, s[16:17]
	v_ldexp_f32 v213, v213, v212
	v_log_f32_e32 v213, v213
	s_nop 0
	v_mul_f32_e32 v212, 0x3f317217, v213
	v_fma_f32 v212, v213, s75, -v212
	v_fmac_f32_e32 v212, 0x3377d1cf, v213
	v_fmac_f32_e32 v212, 0x3f317217, v213
	v_cmp_lt_f32_e64 s[18:19], |v213|, s51
	s_nop 1
	v_cndmask_b32_e64 v213, v213, v212, s[18:19]
	v_cndmask_b32_e64 v212, 0, v233, s[16:17]
	v_sub_f32_e32 v213, v213, v212
	v_sub_f32_e32 v213, v214, v213
	v_fmamk_f32 v126, v213, 0x3d800000, v125
	ds_read_b128 v[180:183], v94 offset:768
	ds_read_b128 v[184:187], v94 offset:784
	ds_read_b128 v[188:191], v94 offset:800
	ds_read_b128 v[192:195], v94 offset:816
	s_waitcnt lgkmcnt(4)
; #define LAS __attribute__((address_space(3)))
; __device__ __forceinline__ float logsigmoid_fast(float x) { return fminf(x, 0.f) - __logf(1.0f + __expf(-fabsf(x))); }
; template <int KIND, int MODE>
; __device__ __forceinline__ void scan_unit(Frame& F, int layer, int h, int vhalf, int grp) {
;     ...
;             float bc[RPT]; float run = 0.f;
; #pragma unroll
;             for (int i = 0; i < RPT; ++i) { const LAS f32x4* lr = (const LAS f32x4*)(X + (tq * RPT + i) * 16); float z = bl;
; #pragma unroll
;                 for (int r = 0; r < 4; ++r) { const f32x4 l4 = lr[r]; z += l4[0] * wl[4 * r] + l4[1] * wl[4 * r + 1] + l4[2] * wl[4 * r + 2] + l4[3] * wl[4 * r + 3]; }
;                 run += logsigmoid_fast(z) * (1.0f / 16.0f); bc[i] = run; }
	v_mul_f32_e32 v212, v76, v197
	v_fmac_f32_e32 v212, v75, v196
	v_fmac_f32_e32 v212, v77, v198
	v_fmac_f32_e32 v212, v78, v199
	v_add_f32_e32 v213, v91, v212
	v_mul_f32_e32 v212, v80, v201
	v_fmac_f32_e32 v212, v79, v200
	v_fmac_f32_e32 v212, v81, v202
	v_fmac_f32_e32 v212, v82, v203
	v_add_f32_e32 v213, v213, v212
	v_mul_f32_e32 v212, v84, v205
	v_fmac_f32_e32 v212, v83, v204
	v_fmac_f32_e32 v212, v85, v206
	v_fmac_f32_e32 v212, v86, v207
	v_add_f32_e32 v213, v213, v212
	v_mul_f32_e32 v212, v88, v209
	v_fmac_f32_e32 v212, v87, v208
	v_fmac_f32_e32 v212, v89, v210
	v_fmac_f32_e32 v212, v90, v211
	v_add_f32_e32 v213, v213, v212
	v_min_f32_e32 v214, 0, v213
	v_mul_f32_e64 v213, |v213|, s65
	v_exp_f32_e32 v213, v213
	s_nop 0
	v_add_f32_e32 v213, 1.0, v213
	v_cmp_gt_f32_e64 s[16:17], s88, v213
	s_nop 1
	v_cndmask_b32_e64 v212, 0, 32, s[16:17]
	v_ldexp_f32 v213, v213, v212
	v_log_f32_e32 v213, v213
	s_nop 0
	v_mul_f32_e32 v212, 0x3f317217, v213
	v_fma_f32 v212, v213, s75, -v212
	v_fmac_f32_e32 v212, 0x3377d1cf, v213
	v_fmac_f32_e32 v212, 0x3f317217, v213
	v_cmp_lt_f32_e64 s[18:19], |v213|, s51
	s_nop 1
	v_cndmask_b32_e64 v213, v213, v212, s[18:19]
	v_cndmask_b32_e64 v212, 0, v233, s[16:17]
	v_sub_f32_e32 v213, v213, v212
	v_sub_f32_e32 v213, v214, v213
	v_fmamk_f32 v127, v213, 0x3d800000, v126
	ds_read_b128 v[196:199], v94 offset:832
	ds_read_b128 v[200:203], v94 offset:848
	ds_read_b128 v[204:207], v94 offset:864
	ds_read_b128 v[208:211], v94 offset:880
	s_waitcnt lgkmcnt(4)
	v_mul_f32_e32 v212, v76, v181
	v_fmac_f32_e32 v212, v75, v180
	v_fmac_f32_e32 v212, v77, v182
	v_fmac_f32_e32 v212, v78, v183
	v_add_f32_e32 v213, v91, v212
	v_mul_f32_e32 v212, v80, v185
	v_fmac_f32_e32 v212, v79, v184
	v_fmac_f32_e32 v212, v81, v186
	v_fmac_f32_e32 v212, v82, v187
	v_add_f32_e32 v213, v213, v212
	v_mul_f32_e32 v212, v84, v189
	v_fmac_f32_e32 v212, v83, v188
	v_fmac_f32_e32 v212, v85, v190
	v_fmac_f32_e32 v212, v86, v191
	v_add_f32_e32 v213, v213, v212
	v_mul_f32_e32 v212, v88, v193
	v_fmac_f32_e32 v212, v87, v192
	v_fmac_f32_e32 v212, v89, v194
	v_fmac_f32_e32 v212, v90, v195
	v_add_f32_e32 v213, v213, v212
	v_min_f32_e32 v214, 0, v213
	v_mul_f32_e64 v213, |v213|, s65
	v_exp_f32_e32 v213, v213
	s_nop 0
	v_add_f32_e32 v213, 1.0, v213
	v_cmp_gt_f32_e64 s[16:17], s88, v213
	s_nop 1
	v_cndmask_b32_e64 v212, 0, 32, s[16:17]
	v_ldexp_f32 v213, v213, v212
	v_log_f32_e32 v213, v213
	s_nop 0
	v_mul_f32_e32 v212, 0x3f317217, v213
	v_fma_f32 v212, v213, s75, -v212
	v_fmac_f32_e32 v212, 0x3377d1cf, v213
	v_fmac_f32_e32 v212, 0x3f317217, v213
	v_cmp_lt_f32_e64 s[18:19], |v213|, s51
	s_nop 1
	v_cndmask_b32_e64 v213, v213, v212, s[18:19]
	v_cndmask_b32_e64 v212, 0, v233, s[16:17]
	v_sub_f32_e32 v213, v213, v212
	v_sub_f32_e32 v213, v214, v213
	v_fmamk_f32 v128, v213, 0x3d800000, v127
	ds_read_b128 v[180:183], v94 offset:896
	ds_read_b128 v[184:187], v94 offset:912
	ds_read_b128 v[188:191], v94 offset:928
	ds_read_b128 v[192:195], v94 offset:944
	s_waitcnt lgkmcnt(4)
	v_mul_f32_e32 v212, v76, v197
	v_fmac_f32_e32 v212, v75, v196
	v_fmac_f32_e32 v212, v77, v198
	v_fmac_f32_e32 v212, v78, v199
	v_add_f32_e32 v213, v91, v212
	v_mul_f32_e32 v212, v80, v201
	v_fmac_f32_e32 v212, v79, v200
	v_fmac_f32_e32 v212, v81, v202
	v_fmac_f32_e32 v212, v82, v203
	v_add_f32_e32 v213, v213, v212
	v_mul_f32_e32 v212, v84, v205
	v_fmac_f32_e32 v212, v83, v204
	v_fmac_f32_e32 v212, v85, v206
	v_fmac_f32_e32 v212, v86, v207
	v_add_f32_e32 v213, v213, v212
	v_mul_f32_e32 v212, v88, v209
	v_fmac_f32_e32 v212, v87, v208
	v_fmac_f32_e32 v212, v89, v210
	v_fmac_f32_e32 v212, v90, v211
	v_add_f32_e32 v213, v213, v212
	v_min_f32_e32 v214, 0, v213
	v_mul_f32_e64 v213, |v213|, s65
	v_exp_f32_e32 v213, v213
	s_nop 0
	v_add_f32_e32 v213, 1.0, v213
	v_cmp_gt_f32_e64 s[16:17], s88, v213
	s_nop 1
	v_cndmask_b32_e64 v212, 0, 32, s[16:17]
	v_ldexp_f32 v213, v213, v212
	v_log_f32_e32 v213, v213
	s_nop 0
	v_mul_f32_e32 v212, 0x3f317217, v213
	v_fma_f32 v212, v213, s75, -v212
	v_fmac_f32_e32 v212, 0x3377d1cf, v213
	v_fmac_f32_e32 v212, 0x3f317217, v213
	v_cmp_lt_f32_e64 s[18:19], |v213|, s51
	s_nop 1
	v_cndmask_b32_e64 v213, v213, v212, s[18:19]
	v_cndmask_b32_e64 v212, 0, v233, s[16:17]
	v_sub_f32_e32 v213, v213, v212
	v_sub_f32_e32 v213, v214, v213
	v_fmamk_f32 v129, v213, 0x3d800000, v128
	ds_read_b128 v[196:199], v94 offset:960
	ds_read_b128 v[200:203], v94 offset:976
	ds_read_b128 v[204:207], v94 offset:992
	ds_read_b128 v[208:211], v94 offset:1008
	s_waitcnt lgkmcnt(4)
	v_mul_f32_e32 v212, v76, v181
	v_fmac_f32_e32 v212, v75, v180
	v_fmac_f32_e32 v212, v77, v182
	v_fmac_f32_e32 v212, v78, v183
	v_add_f32_e32 v213, v91, v212
	v_mul_f32_e32 v212, v80, v185
	v_fmac_f32_e32 v212, v79, v184
	v_fmac_f32_e32 v212, v81, v186
	v_fmac_f32_e32 v212, v82, v187
	v_add_f32_e32 v213, v213, v212
	v_mul_f32_e32 v212, v84, v189
	v_fmac_f32_e32 v212, v83, v188
	v_fmac_f32_e32 v212, v85, v190
	v_fmac_f32_e32 v212, v86, v191
	v_add_f32_e32 v213, v213, v212
	v_mul_f32_e32 v212, v88, v193
	v_fmac_f32_e32 v212, v87, v192
	v_fmac_f32_e32 v212, v89, v194
	v_fmac_f32_e32 v212, v90, v195
	v_add_f32_e32 v213, v213, v212
	v_min_f32_e32 v214, 0, v213
	v_mul_f32_e64 v213, |v213|, s65
	v_exp_f32_e32 v213, v213
	s_nop 0
	v_add_f32_e32 v213, 1.0, v213
	v_cmp_gt_f32_e64 s[16:17], s88, v213
	s_nop 1
	v_cndmask_b32_e64 v212, 0, 32, s[16:17]
	v_ldexp_f32 v213, v213, v212
	v_log_f32_e32 v213, v213
	s_nop 0
	v_mul_f32_e32 v212, 0x3f317217, v213
	v_fma_f32 v212, v213, s75, -v212
	v_fmac_f32_e32 v212, 0x3377d1cf, v213
	v_fmac_f32_e32 v212, 0x3f317217, v213
	v_cmp_lt_f32_e64 s[18:19], |v213|, s51
	s_nop 1
	v_cndmask_b32_e64 v213, v213, v212, s[18:19]
	v_cndmask_b32_e64 v212, 0, v233, s[16:17]
	v_sub_f32_e32 v213, v213, v212
	v_sub_f32_e32 v213, v214, v213
	v_fmamk_f32 v131, v213, 0x3d800000, v129
	s_waitcnt lgkmcnt(0)
; #define LAS __attribute__((address_space(3)))
; __device__ __forceinline__ float logsigmoid_fast(float x) { return fminf(x, 0.f) - __logf(1.0f + __expf(-fabsf(x))); }
; template <int KIND, int MODE>
; __device__ __forceinline__ void scan_unit(Frame& F, int layer, int h, int vhalf, int grp) {
;     ...
;             for (int i = 0; i < RPT; ++i) { const LAS f32x4* lr = (const LAS f32x4*)(X + (tq * RPT + i) * 16); float z = bl;
; #pragma unroll
;                 for (int r = 0; r < 4; ++r) { const f32x4 l4 = lr[r]; z += l4[0] * wl[4 * r] + l4[1] * wl[4 * r + 1] + l4[2] * wl[4 * r + 2] + l4[3] * wl[4 * r + 3]; }
;                 run += logsigmoid_fast(z) * (1.0f / 16.0f); bc[i] = run; }
;             X[1024 + tq * 128 + d] = run;
;             __syncthreads();
	v_mul_f32_e32 v212, v76, v197
	v_fmac_f32_e32 v212, v75, v196
	v_fmac_f32_e32 v212, v77, v198
	v_fmac_f32_e32 v212, v78, v199
	v_add_f32_e32 v213, v91, v212
	v_mul_f32_e32 v212, v80, v201
	v_fmac_f32_e32 v212, v79, v200
	v_fmac_f32_e32 v212, v81, v202
	v_fmac_f32_e32 v212, v82, v203
	v_add_f32_e32 v213, v213, v212
	v_mul_f32_e32 v212, v84, v205
	v_fmac_f32_e32 v212, v83, v204
	v_fmac_f32_e32 v212, v85, v206
	v_fmac_f32_e32 v212, v86, v207
	v_add_f32_e32 v213, v213, v212
	v_mul_f32_e32 v212, v88, v209
	v_fmac_f32_e32 v212, v87, v208
	v_fmac_f32_e32 v212, v89, v210
	v_fmac_f32_e32 v212, v90, v211
	v_add_f32_e32 v213, v213, v212
	v_min_f32_e32 v214, 0, v213
	v_mul_f32_e64 v213, |v213|, s65
	v_exp_f32_e32 v213, v213
	s_nop 0
	v_add_f32_e32 v213, 1.0, v213
	v_cmp_gt_f32_e64 s[16:17], s88, v213
	s_nop 1
	v_cndmask_b32_e64 v212, 0, 32, s[16:17]
	v_ldexp_f32 v213, v213, v212
	v_log_f32_e32 v213, v213
	s_nop 0
	v_mul_f32_e32 v212, 0x3f317217, v213
	v_fma_f32 v212, v213, s75, -v212
	v_fmac_f32_e32 v212, 0x3377d1cf, v213
	v_fmac_f32_e32 v212, 0x3f317217, v213
	v_cmp_lt_f32_e64 s[18:19], |v213|, s51
	s_nop 1
	v_cndmask_b32_e64 v213, v213, v212, s[18:19]
	v_cndmask_b32_e64 v212, 0, v233, s[16:17]
	v_sub_f32_e32 v213, v213, v212
	v_sub_f32_e32 v213, v214, v213
	v_fmamk_f32 v132, v213, 0x3d800000, v131
	ds_write_b32 v96, v132 offset:4096
	s_waitcnt lgkmcnt(0)
	s_barrier
; __device__ __forceinline__ unsigned pk2hw(float lo, float hi) { unsigned r; asm("s_nop 1\n\tv_cvt_pk_bf16_f32 %0, %1, %2" : "=v"(r) : "v"(lo), "v"(hi)); return r; }
; template <int KIND, int MODE>
; __device__ __forceinline__ void scan_unit(Frame& F, int layer, int h, int vhalf, int grp) {
;     ...
;             float pre = 0.f, tot = 0.f;
; #pragma unroll
;             for (int qq = 0; qq < NTQ; ++qq) { const float v = X[1024 + qq * 128 + d]; tot += v; if (qq < tq) pre += v; }
;             const float etot = __expf(tot);
;             if (tq == 0) { X[1536 + d] = etot; gtot += tot; }
; #pragma unroll
;             for (int i = 0; i < RPT; ++i) { const int t = tq * RPT + i; const float bcv = bc[i] + pre;
;                 const float kv = bf2f(KS[t * QST + d]); const float eb = __expf(bcv), ib = __builtin_amdgcn_rcpf(eb);
;                 if (MODE == 1) { const float qv = bf2f(QS[t * QST + d]); const unsigned w0 = pk2hw(qv * 0.08838834764831845f * eb, kv * ib); QS[t * QST + d] = (unsigned short)w0; KS[t * QST + d] = (unsigned short)(w0 >> 16); }
;                 K2[t * QST + d] = (unsigned short)pk2hw(kv * (etot * ib), 0.f); }
;             if (PREF && ch + 1 < (grp + 1) * GC) SCAN_LOAD(tb + 64);
	ds_read_b32 v130, v99
	ds_read_b32 v134, v101
	ds_read_b32 v135, v102
	ds_read_b32 v136, v103
	s_waitcnt lgkmcnt(3)
	v_add_f32_e32 v133, 0, v130
	s_waitcnt lgkmcnt(2)
	v_add_f32_e32 v130, v133, v134
	s_waitcnt lgkmcnt(1)
	v_add_f32_e32 v130, v130, v135
	s_waitcnt lgkmcnt(0)
	v_add_f32_e32 v137, v130, v136
	v_mul_f32_e32 v130, 0x3fb8aa3b, v137
	v_exp_f32_e32 v130, v130
	s_and_saveexec_b64 s[0:1], vcc
	v_add_f32_e32 v100, v100, v137
	ds_write_b32 v95, v130 offset:6144
	s_or_b64 exec, exec, s[0:1]
	v_cndmask_b32_e64 v133, 0, v133, s[8:9]
	v_add_f32_e32 v134, v134, v133
	v_cndmask_b32_e64 v133, v133, v134, s[10:11]
	v_add_f32_e32 v134, v135, v133
	v_cndmask_b32_e64 v133, v133, v134, s[12:13]
	v_add_f32_e32 v134, v136, v133
	v_cndmask_b32_e64 v133, v133, v134, s[14:15]
	v_add_f32_e32 v50, v50, v133
	v_mul_f32_e32 v50, 0x3fb8aa3b, v50
	v_exp_f32_e32 v50, v50
	ds_read_u16 v134, v104 offset:33792
	s_cmp_ge_i32 s24, s23
	v_rcp_f32_e32 v50, v50
	s_waitcnt lgkmcnt(0)
	v_lshlrev_b32_e32 v134, 16, v134
	v_mul_f32_e32 v50, v130, v50
	v_mul_f32_e32 v50, v50, v134
	s_nop 1
	v_cvt_pk_bf16_f32 v50, v50, v1
	ds_write_b16 v105, v50
	v_add_f32_e32 v50, v51, v133
	v_mul_f32_e32 v50, 0x3fb8aa3b, v50
	v_exp_f32_e32 v50, v50
	ds_read_u16 v51, v104 offset:34064
	v_rcp_f32_e32 v50, v50
	s_waitcnt lgkmcnt(0)
	v_lshlrev_b32_e32 v51, 16, v51
	v_mul_f32_e32 v50, v130, v50
	v_mul_f32_e32 v50, v50, v51
	s_nop 1
	v_cvt_pk_bf16_f32 v50, v50, v1
	ds_write_b16 v106, v50
	v_add_f32_e32 v50, v52, v133
	v_mul_f32_e32 v50, 0x3fb8aa3b, v50
	v_exp_f32_e32 v50, v50
	ds_read_u16 v51, v104 offset:34336
	v_rcp_f32_e32 v50, v50
	s_waitcnt lgkmcnt(0)
	v_lshlrev_b32_e32 v51, 16, v51
	v_mul_f32_e32 v50, v130, v50
	v_mul_f32_e32 v50, v50, v51
	s_nop 1
	v_cvt_pk_bf16_f32 v50, v50, v1
	ds_write_b16 v107, v50
	v_add_f32_e32 v50, v53, v133
	v_mul_f32_e32 v50, 0x3fb8aa3b, v50
	v_exp_f32_e32 v50, v50
	ds_read_u16 v51, v104 offset:34608
	v_rcp_f32_e32 v50, v50
	s_waitcnt lgkmcnt(0)
	v_lshlrev_b32_e32 v51, 16, v51
	v_mul_f32_e32 v50, v130, v50
	v_mul_f32_e32 v50, v50, v51
	s_nop 1
	v_cvt_pk_bf16_f32 v50, v50, v1
	ds_write_b16 v108, v50
	v_add_f32_e32 v50, v54, v133
	v_mul_f32_e32 v50, 0x3fb8aa3b, v50
	v_exp_f32_e32 v50, v50
	ds_read_u16 v51, v104 offset:34880
	v_rcp_f32_e32 v50, v50
	s_waitcnt lgkmcnt(0)
	v_lshlrev_b32_e32 v51, 16, v51
	v_mul_f32_e32 v50, v130, v50
	v_mul_f32_e32 v50, v50, v51
	s_nop 1
	v_cvt_pk_bf16_f32 v50, v50, v1
	ds_write_b16 v109, v50
	v_add_f32_e32 v50, v55, v133
	v_mul_f32_e32 v50, 0x3fb8aa3b, v50
	v_exp_f32_e32 v50, v50
	ds_read_u16 v51, v104 offset:35152
	v_rcp_f32_e32 v50, v50
	s_waitcnt lgkmcnt(0)
	v_lshlrev_b32_e32 v51, 16, v51
	v_mul_f32_e32 v50, v130, v50
	v_mul_f32_e32 v50, v50, v51
	s_nop 1
	v_cvt_pk_bf16_f32 v50, v50, v1
	ds_write_b16 v110, v50
	v_add_f32_e32 v50, v56, v133
	v_mul_f32_e32 v50, 0x3fb8aa3b, v50
	v_exp_f32_e32 v50, v50
	ds_read_u16 v51, v104 offset:35424
	v_rcp_f32_e32 v50, v50
	s_waitcnt lgkmcnt(0)
	v_lshlrev_b32_e32 v51, 16, v51
	v_mul_f32_e32 v50, v130, v50
	v_mul_f32_e32 v50, v50, v51
	s_nop 1
	v_cvt_pk_bf16_f32 v50, v50, v1
	ds_write_b16 v111, v50
	v_add_f32_e32 v50, v124, v133
	v_mul_f32_e32 v50, 0x3fb8aa3b, v50
	v_exp_f32_e32 v50, v50
	ds_read_u16 v51, v104 offset:35696
	v_rcp_f32_e32 v50, v50
	s_waitcnt lgkmcnt(0)
	v_lshlrev_b32_e32 v51, 16, v51
	v_mul_f32_e32 v50, v130, v50
	v_mul_f32_e32 v50, v50, v51
	s_nop 1
	v_cvt_pk_bf16_f32 v50, v50, v1
	ds_write_b16 v112, v50
	v_add_f32_e32 v50, v57, v133
	v_mul_f32_e32 v50, 0x3fb8aa3b, v50
	v_exp_f32_e32 v50, v50
	ds_read_u16 v51, v104 offset:35968
	v_rcp_f32_e32 v50, v50
	s_waitcnt lgkmcnt(0)
	v_lshlrev_b32_e32 v51, 16, v51
	v_mul_f32_e32 v50, v130, v50
	v_mul_f32_e32 v50, v50, v51
	s_nop 1
	v_cvt_pk_bf16_f32 v50, v50, v1
	ds_write_b16 v113, v50
	v_add_f32_e32 v50, v125, v133
	v_mul_f32_e32 v50, 0x3fb8aa3b, v50
	v_exp_f32_e32 v50, v50
	ds_read_u16 v51, v104 offset:36240
	v_rcp_f32_e32 v50, v50
	s_waitcnt lgkmcnt(0)
	v_lshlrev_b32_e32 v51, 16, v51
	v_mul_f32_e32 v50, v130, v50
	v_mul_f32_e32 v50, v50, v51
	s_nop 1
	v_cvt_pk_bf16_f32 v50, v50, v1
	ds_write_b16 v114, v50
	v_add_f32_e32 v50, v126, v133
	v_mul_f32_e32 v50, 0x3fb8aa3b, v50
	v_exp_f32_e32 v50, v50
	ds_read_u16 v51, v104 offset:36512
	v_rcp_f32_e32 v50, v50
	s_waitcnt lgkmcnt(0)
	v_lshlrev_b32_e32 v51, 16, v51
	v_mul_f32_e32 v50, v130, v50
	v_mul_f32_e32 v50, v50, v51
	s_nop 1
	v_cvt_pk_bf16_f32 v50, v50, v1
	ds_write_b16 v115, v50
	v_add_f32_e32 v50, v127, v133
	v_mul_f32_e32 v50, 0x3fb8aa3b, v50
	v_exp_f32_e32 v50, v50
	ds_read_u16 v51, v104 offset:36784
	v_rcp_f32_e32 v50, v50
	s_waitcnt lgkmcnt(0)
	v_lshlrev_b32_e32 v51, 16, v51
	v_mul_f32_e32 v50, v130, v50
	v_mul_f32_e32 v50, v50, v51
	s_nop 1
	v_cvt_pk_bf16_f32 v50, v50, v1
	ds_write_b16 v116, v50
	v_add_f32_e32 v50, v128, v133
	v_mul_f32_e32 v50, 0x3fb8aa3b, v50
	v_exp_f32_e32 v50, v50
	ds_read_u16 v51, v104 offset:37056
	v_rcp_f32_e32 v50, v50
	s_waitcnt lgkmcnt(0)
	v_lshlrev_b32_e32 v51, 16, v51
	v_mul_f32_e32 v50, v130, v50
	v_mul_f32_e32 v50, v50, v51
	s_nop 1
	v_cvt_pk_bf16_f32 v50, v50, v1
	ds_write_b16 v117, v50
	v_add_f32_e32 v50, v129, v133
	v_mul_f32_e32 v50, 0x3fb8aa3b, v50
	v_exp_f32_e32 v50, v50
	ds_read_u16 v51, v104 offset:37328
	v_rcp_f32_e32 v50, v50
	s_waitcnt lgkmcnt(0)
	v_lshlrev_b32_e32 v51, 16, v51
	v_mul_f32_e32 v50, v130, v50
	v_mul_f32_e32 v50, v50, v51
	s_nop 1
	v_cvt_pk_bf16_f32 v50, v50, v1
	ds_write_b16 v118, v50
	v_add_f32_e32 v50, v131, v133
	v_mul_f32_e32 v50, 0x3fb8aa3b, v50
	v_exp_f32_e32 v50, v50
	ds_read_u16 v51, v104 offset:37600
	v_rcp_f32_e32 v50, v50
	s_waitcnt lgkmcnt(0)
	v_lshlrev_b32_e32 v51, 16, v51
	v_mul_f32_e32 v50, v130, v50
	v_mul_f32_e32 v50, v50, v51
	s_nop 1
	v_cvt_pk_bf16_f32 v50, v50, v1
	ds_write_b16 v119, v50
	v_add_f32_e32 v50, v133, v132
	v_mul_f32_e32 v50, 0x3fb8aa3b, v50
	v_exp_f32_e32 v50, v50
	ds_read_u16 v51, v104 offset:37872
	v_rcp_f32_e32 v50, v50
	s_waitcnt lgkmcnt(0)
	v_lshlrev_b32_e32 v51, 16, v51
	v_mul_f32_e32 v50, v130, v50
	v_mul_f32_e32 v50, v50, v51
	s_nop 1
	v_cvt_pk_bf16_f32 v50, v50, v1
	ds_write_b16 v120, v50
	s_cbranch_scc1 .LBB0_423
	v_lshl_add_u64 v[2:3], v[72:73], 0, s[20:21]
	v_lshl_add_u64 v[6:7], v[66:67], 0, s[20:21]
	flat_load_dwordx4 v[2:5], v[2:3]
	s_nop 0
	flat_load_dwordx4 v[6:9], v[6:7]
	v_lshl_add_u64 v[10:11], v[70:71], 0, s[20:21]
	v_lshl_add_u64 v[14:15], v[64:65], 0, s[20:21]
	v_lshl_add_u64 v[12:13], v[68:69], 0, s[20:21]
	v_lshl_add_u64 v[16:17], v[62:63], 0, s[20:21]
	flat_load_ushort v50, v[16:17]
	flat_load_ushort v51, v[12:13]
	s_nop 0
	flat_load_dwordx4 v[10:13], v[10:11]
	s_nop 0
	flat_load_dwordx4 v[14:17], v[14:15]
	s_waitcnt vmcnt(0) lgkmcnt(0)
	v_lshlrev_b32_e32 v60, 16, v50
	v_lshlrev_b32_e32 v61, 16, v51
	s_branch .LBB0_423

; template <int KIND, int MODE>
; __device__ __forceinline__ void scan_unit(Frame& F, int layer, int h, int vhalf, int grp) {
;     ...
;             const bf16_t* mq = WSP(bf16_t, OFF_MQ) + h * 256; const bf16_t* mk = WSP(bf16_t, OFF_MK) + h * 256;
;             u32x4 qr[4];
; #pragma unroll
;             for (int i = 0; i < 4; ++i) { const int c = tid + 512 * i, t = c >> 5, dc = (c & 31) * 8; if (MODE == 1) qr[i] = *(const u32x4*)(mq + (size_t)(tb + t) * D + dc); }
;             if (w == 0) {
;                 const float lf = pl0, lin = pl1; const float mst = X[321];
;                 float bb = lf;
; #pragma unroll
;                 for (int o = 1; o < 64; o <<= 1) { const float n = __shfl_up(bb, o); if (lane >= o) bb += n; }
;                 const float c = lin - bb; float cm = c;
; #pragma unroll
;                 for (int o = 1; o < 64; o <<= 1) { const float n = __shfl_up(cm, o); if (lane >= o) cm = fmaxf(cm, n); }
;                 const float Mt = fmaxf(mst, cm); const float gsum = __shfl(bb, 63), M63 = __shfl(Mt, 63);
;                 X[lane] = c; X[64 + lane] = Mt; X[128 + lane] = __expf(mst - Mt); X[192 + lane] = __expf(c - M63); X[256 + lane] = __expf(-(bb + Mt));
;                 if (lane == 0) { X[320] = __expf(mst - M63); X[321] = gsum + M63; X[322] += gsum; }
.LBB0_526:
	s_lshl_b32 s44, s62, 6
	v_add_u32_e32 v68, s44, v135
	v_add_u32_e32 v70, s44, v136
	v_ashrrev_i32_e32 v69, 31, v68
	v_ashrrev_i32_e32 v71, 31, v70
	v_lshlrev_b64 v[68:69], 11, v[68:69]
	v_lshlrev_b64 v[70:71], 11, v[70:71]
	v_lshl_add_u64 v[68:69], v[118:119], 0, v[68:69]
	v_lshl_add_u64 v[70:71], v[118:119], 0, v[70:71]
	flat_load_dwordx4 v[72:75], v[68:69]
	flat_load_dwordx4 v[80:83], v[70:71]
	v_add_u32_e32 v68, s44, v137
	v_add_u32_e32 v70, s44, v138
	v_ashrrev_i32_e32 v69, 31, v68
	v_ashrrev_i32_e32 v71, 31, v70
	v_lshlrev_b64 v[88:89], 11, v[68:69]
	v_lshlrev_b64 v[90:91], 11, v[70:71]
	v_lshl_add_u64 v[68:69], v[122:123], 0, v[88:89]
	v_lshl_add_u64 v[70:71], v[122:123], 0, v[90:91]
	flat_load_dwordx4 v[92:95], v[68:69]
	flat_load_dwordx4 v[84:87], v[70:71]
	v_add_u32_e32 v68, s44, v139
	v_add_u32_e32 v70, s44, v140
	v_ashrrev_i32_e32 v69, 31, v68
	v_ashrrev_i32_e32 v71, 31, v70
	v_lshlrev_b64 v[100:101], 11, v[68:69]
	v_lshlrev_b64 v[102:103], 11, v[70:71]
	v_lshl_add_u64 v[68:69], v[122:123], 0, v[100:101]
	v_lshl_add_u64 v[70:71], v[122:123], 0, v[102:103]
	flat_load_dwordx4 v[76:79], v[68:69]
	s_nop 0
	flat_load_dwordx4 v[68:71], v[70:71]
	v_lshl_add_u64 v[250:251], v[124:125], 0, v[88:89]
	global_load_dwordx4 v[234:237], v[250:251], off
	v_lshl_add_u64 v[250:251], v[124:125], 0, v[90:91]
	global_load_dwordx4 v[238:241], v[250:251], off
	v_lshl_add_u64 v[250:251], v[124:125], 0, v[100:101]
	global_load_dwordx4 v[242:245], v[250:251], off
	v_lshl_add_u64 v[250:251], v[124:125], 0, v[102:103]
	global_load_dwordx4 v[246:249], v[250:251], off
	v_cndmask_b32_e64 v0, 0, 1, s[90:91]
	v_cmp_ne_u32_e64 s[42:43], 1, v0
	s_andn2_b64 vcc, exec, s[90:91]
	s_cbranch_vccnz .LBB0_528
	v_or_b32_e32 v96, s44, v126
	v_ashrrev_i32_e32 v97, 31, v96
	v_lshlrev_b64 v[96:97], 5, v[96:97]
	v_lshl_add_u64 v[96:97], s[72:73], 0, v[96:97]
	flat_load_dword v203, v[96:97] offset:16
	flat_load_dword v207, v[96:97]
.LBB0_528:
	s_waitcnt vmcnt(0) lgkmcnt(0)
	ds_write_b128 v196, v[72:75]
	ds_write_b128 v197, v[80:83]
	v_lshl_add_u64 v[72:73], v[124:125], 0, v[88:89]
	v_lshl_add_u64 v[74:75], v[124:125], 0, v[90:91]
	v_mov_b32_e32 v96, v234
	v_mov_b32_e32 v97, v235
	v_mov_b32_e32 v98, v236
	v_mov_b32_e32 v99, v237
	v_mov_b32_e32 v88, v238
	v_mov_b32_e32 v89, v239
	v_mov_b32_e32 v90, v240
	v_mov_b32_e32 v91, v241
	v_lshl_add_u64 v[72:73], v[124:125], 0, v[100:101]
	v_lshl_add_u64 v[74:75], v[124:125], 0, v[102:103]
	v_mov_b32_e32 v80, v242
	v_mov_b32_e32 v81, v243
	v_mov_b32_e32 v82, v244
	v_mov_b32_e32 v83, v245
	s_nop 0
	v_mov_b32_e32 v72, v246
	v_mov_b32_e32 v73, v247
	v_mov_b32_e32 v74, v248
	v_mov_b32_e32 v75, v249
	s_and_b64 vcc, exec, s[42:43]
	s_cbranch_vccnz .LBB0_532
	v_readlane_b32 s0, v253, 39
	s_nop 1
	v_mov_b32_e32 v0, s0
	ds_read_b32 v102, v0
	ds_bpermute_b32 v0, v141, v203
	s_waitcnt lgkmcnt(0)
	v_add_f32_e32 v0, v203, v0
	v_cndmask_b32_e64 v0, v0, v203, s[10:11]
	ds_bpermute_b32 v100, v142, v0
	s_waitcnt lgkmcnt(0)
	v_add_f32_e32 v100, v0, v100
	v_cndmask_b32_e64 v0, v100, v0, s[16:17]
	ds_bpermute_b32 v100, v143, v0
	s_waitcnt lgkmcnt(0)
	v_add_f32_e32 v100, v0, v100
	v_cndmask_b32_e64 v0, v100, v0, s[18:19]
	ds_bpermute_b32 v100, v144, v0
	s_waitcnt lgkmcnt(0)
	v_add_f32_e32 v100, v0, v100
	v_cndmask_b32_e64 v0, v100, v0, s[20:21]
	ds_bpermute_b32 v100, v145, v0
	s_waitcnt lgkmcnt(0)
	v_add_f32_e32 v100, v0, v100
	v_cndmask_b32_e64 v0, v100, v0, s[12:13]
	ds_bpermute_b32 v100, v147, v0
	s_waitcnt lgkmcnt(0)
	v_add_f32_e32 v100, v0, v100
	v_cndmask_b32_e64 v101, v100, v0, s[22:23]
	v_sub_f32_e32 v103, v207, v101
	ds_bpermute_b32 v0, v141, v103
	s_waitcnt lgkmcnt(0)
	v_max_f32_e32 v0, v0, v0
	v_max_f32_e32 v0, v103, v0
	v_cndmask_b32_e64 v0, v0, v103, s[10:11]
	ds_bpermute_b32 v100, v142, v0
	s_waitcnt lgkmcnt(0)
	v_max_f32_e32 v100, v100, v100
	v_max_f32_e32 v100, v0, v100
	v_cndmask_b32_e64 v0, v100, v0, s[16:17]
	ds_bpermute_b32 v100, v143, v0
	s_waitcnt lgkmcnt(0)
	v_max_f32_e32 v100, v100, v100
	v_max_f32_e32 v100, v0, v100
	v_cndmask_b32_e64 v0, v100, v0, s[18:19]
	ds_bpermute_b32 v100, v144, v0
	s_waitcnt lgkmcnt(0)
	v_max_f32_e32 v100, v100, v100
	v_max_f32_e32 v100, v0, v100
	v_cndmask_b32_e64 v0, v100, v0, s[20:21]
	ds_bpermute_b32 v100, v145, v0
	s_waitcnt lgkmcnt(0)
	v_max_f32_e32 v100, v100, v100
	v_max_f32_e32 v100, v0, v100
	v_cndmask_b32_e64 v0, v100, v0, s[12:13]
	ds_bpermute_b32 v100, v147, v0
	v_max_f32_e32 v104, v0, v0
	s_waitcnt lgkmcnt(0)
	v_max_f32_e32 v100, v100, v100
	v_max_f32_e32 v100, v104, v100
	v_cndmask_b32_e64 v0, v100, v0, s[22:23]
	v_max_f32_e32 v0, v0, v0
	v_max_f32_e32 v100, v102, v102
	v_max_f32_e32 v104, v100, v0
	ds_bpermute_b32 v100, v232, v104
	ds_bpermute_b32 v0, v232, v101
	ds_write2st64_b32 v127, v103, v104 offset1:1
	v_sub_f32_e32 v105, v102, v104
	v_add_f32_e32 v101, v101, v104
	s_waitcnt lgkmcnt(0)
	v_sub_f32_e32 v103, v103, v100
	v_mul_f32_e32 v105, 0x3fb8aa3b, v105
	v_mul_f32_e32 v103, 0x3fb8aa3b, v103
	v_mul_f32_e32 v101, 0xbfb8aa3b, v101
	v_exp_f32_e32 v105, v105
	v_exp_f32_e32 v103, v103
	v_exp_f32_e32 v101, v101
	ds_write2st64_b32 v127, v105, v103 offset0:2 offset1:3
	ds_write_b32 v127, v101 offset:1024
	s_and_saveexec_b64 s[0:1], s[10:11]
	s_cbranch_execz .LBB0_531
	v_readlane_b32 s4, v253, 40
	v_sub_f32_e32 v102, v102, v100
	v_mul_f32_e32 v102, 0x3fb8aa3b, v102
	v_mov_b32_e32 v101, s4
	ds_read_b32 v101, v101
	v_exp_f32_e32 v102, v102
	s_waitcnt lgkmcnt(0)
	v_pk_add_f32 v[100:101], v[0:1], v[100:101] op_sel_hi:[0,1]
	v_mov_b32_e32 v103, v100
	v_mov_b32_e32 v104, v101
	v_mov_b32_e32 v0, s83
	ds_write_b96 v0, v[102:104]

; #define LAS __attribute__((address_space(3)))
; __device__ __forceinline__ float logsigmoid_fast(float x) { return fminf(x, 0.f) - __logf(1.0f + __expf(-fabsf(x))); }
; template <int KIND, int MODE>
; __device__ __forceinline__ void scan_unit(Frame& F, int layer, int h, int vhalf, int grp) {
;     ...
;         for (int i = 0; i < 2; ++i) { const int e = tid + 512 * i; *(LAS u32x4*)(VS + (e >> 4) * VST + (e & 15) * 8) = pv[i]; }
;         if (KIND == 0) {
; #pragma unroll
;             for (int i = 0; i < 2; ++i) { const int c = tid + 512 * i, t = c >> 4, dc = (c & 15) * 8; const bf16_t* rp = proj + (size_t)(tb + t) * NP + h * 128 + dc;
;                 if (MODE == 1) *(LAS u32x4*)(QS + t * QST + dc) = pq[i];
;                 *(LAS u32x4*)(KS + t * QST + dc) = pk[i]; }
;             X[tid] = pl0; X[tid + 512] = pl1;
;             __syncthreads();
;             float bc[RPT]; float run = 0.f;
; #pragma unroll
;             for (int i = 0; i < RPT; ++i) { const LAS f32x4* lr = (const LAS f32x4*)(X + (tq * RPT + i) * 16); float z = bl;
; #pragma unroll
;                 for (int r = 0; r < 4; ++r) { const f32x4 l4 = lr[r]; z += l4[0] * wl[4 * r] + l4[1] * wl[4 * r + 1] + l4[2] * wl[4 * r + 2] + l4[3] * wl[4 * r + 3]; }
;                 run += logsigmoid_fast(z) * (1.0f / 16.0f); bc[i] = run; }
.LBB0_558:
	v_add_u32_e32 v58, v113, v117
	ds_write_b128 v58, v[34:37]
	v_add_u32_e32 v58, v113, v118
	ds_write_b128 v58, v[38:41]
	ds_write_b128 v119, v[50:53]
	ds_write_b128 v119, v[54:57] offset:33792
	ds_write_b128 v120, v[42:45]
	ds_write_b128 v120, v[46:49] offset:33792
	ds_write2st64_b32 v111, v89, v90 offset1:8
	s_waitcnt lgkmcnt(0)
	s_barrier
	ds_read_b128 v[180:183], v110
	ds_read_b128 v[184:187], v110 offset:16
	ds_read_b128 v[188:191], v110 offset:32
	ds_read_b128 v[192:195], v110 offset:48
	ds_read_b128 v[196:199], v110 offset:64
	ds_read_b128 v[200:203], v110 offset:80
	ds_read_b128 v[204:207], v110 offset:96
	ds_read_b128 v[208:211], v110 offset:112
	s_waitcnt lgkmcnt(4)
	v_mul_f32_e32 v212, v94, v181
	v_fmac_f32_e32 v212, v91, v180
	v_fmac_f32_e32 v212, v95, v182
	v_fmac_f32_e32 v212, v96, v183
	v_add_f32_e32 v213, v109, v212
	v_mul_f32_e32 v212, v98, v185
	v_fmac_f32_e32 v212, v97, v184
	v_fmac_f32_e32 v212, v99, v186
	v_fmac_f32_e32 v212, v100, v187
	v_add_f32_e32 v213, v213, v212
	v_mul_f32_e32 v212, v102, v189
	v_fmac_f32_e32 v212, v101, v188
	v_fmac_f32_e32 v212, v103, v190
	v_fmac_f32_e32 v212, v104, v191
	v_add_f32_e32 v213, v213, v212
	v_mul_f32_e32 v212, v106, v193
	v_fmac_f32_e32 v212, v105, v192
	v_fmac_f32_e32 v212, v107, v194
	v_fmac_f32_e32 v212, v108, v195
	v_add_f32_e32 v213, v213, v212
	v_min_f32_e32 v214, 0, v213
	v_mul_f32_e64 v213, |v213|, s65
	v_exp_f32_e32 v213, v213
	s_nop 0
	v_add_f32_e32 v213, 1.0, v213
	v_cmp_gt_f32_e32 vcc, s88, v213
	s_nop 1
	v_cndmask_b32_e64 v212, 0, 32, vcc
	v_ldexp_f32 v213, v213, v212
	v_log_f32_e32 v213, v213
	s_nop 0
	v_mul_f32_e32 v212, 0x3f317217, v213
	v_fma_f32 v212, v213, s75, -v212
	v_fmac_f32_e32 v212, 0x3377d1cf, v213
	v_fmac_f32_e32 v212, 0x3f317217, v213
	v_cmp_lt_f32_e64 s[40:41], |v213|, s51
	s_nop 1
	v_cndmask_b32_e64 v213, v213, v212, s[40:41]
	v_cndmask_b32_e32 v212, 0, v233, vcc
	v_sub_f32_e32 v213, v213, v212
	v_sub_f32_e32 v213, v214, v213
	v_fma_f32 v58, v213, s64, 0
	ds_read_b128 v[180:183], v110 offset:128
	ds_read_b128 v[184:187], v110 offset:144
	ds_read_b128 v[188:191], v110 offset:160
	ds_read_b128 v[192:195], v110 offset:176
	s_waitcnt lgkmcnt(4)
	v_mul_f32_e32 v212, v94, v197
	v_fmac_f32_e32 v212, v91, v196
	v_fmac_f32_e32 v212, v95, v198
	v_fmac_f32_e32 v212, v96, v199
	v_add_f32_e32 v213, v109, v212
	v_mul_f32_e32 v212, v98, v201
	v_fmac_f32_e32 v212, v97, v200
	v_fmac_f32_e32 v212, v99, v202
	v_fmac_f32_e32 v212, v100, v203
	v_add_f32_e32 v213, v213, v212
	v_mul_f32_e32 v212, v102, v205
	v_fmac_f32_e32 v212, v101, v204
	v_fmac_f32_e32 v212, v103, v206
	v_fmac_f32_e32 v212, v104, v207
	v_add_f32_e32 v213, v213, v212
	v_mul_f32_e32 v212, v106, v209
	v_fmac_f32_e32 v212, v105, v208
	v_fmac_f32_e32 v212, v107, v210
	v_fmac_f32_e32 v212, v108, v211
	v_add_f32_e32 v213, v213, v212
	v_min_f32_e32 v214, 0, v213
	v_mul_f32_e64 v213, |v213|, s65
	v_exp_f32_e32 v213, v213
	s_nop 0
	v_add_f32_e32 v213, 1.0, v213
	v_cmp_gt_f32_e32 vcc, s88, v213
	s_nop 1
	v_cndmask_b32_e64 v212, 0, 32, vcc
	v_ldexp_f32 v213, v213, v212
	v_log_f32_e32 v213, v213
	s_nop 0
	v_mul_f32_e32 v212, 0x3f317217, v213
	v_fma_f32 v212, v213, s75, -v212
	v_fmac_f32_e32 v212, 0x3377d1cf, v213
	v_fmac_f32_e32 v212, 0x3f317217, v213
	v_cmp_lt_f32_e64 s[40:41], |v213|, s51
	s_nop 1
	v_cndmask_b32_e64 v213, v213, v212, s[40:41]
	v_cndmask_b32_e32 v212, 0, v233, vcc
	v_sub_f32_e32 v213, v213, v212
	v_sub_f32_e32 v213, v214, v213
	v_fmamk_f32 v59, v213, 0x3d800000, v58
	ds_read_b128 v[196:199], v110 offset:192
	ds_read_b128 v[200:203], v110 offset:208
	ds_read_b128 v[204:207], v110 offset:224
	ds_read_b128 v[208:211], v110 offset:240
	s_waitcnt lgkmcnt(4)
	v_mul_f32_e32 v212, v94, v181
	v_fmac_f32_e32 v212, v91, v180
	v_fmac_f32_e32 v212, v95, v182
	v_fmac_f32_e32 v212, v96, v183
	v_add_f32_e32 v213, v109, v212
	v_mul_f32_e32 v212, v98, v185
	v_fmac_f32_e32 v212, v97, v184
	v_fmac_f32_e32 v212, v99, v186
	v_fmac_f32_e32 v212, v100, v187
	v_add_f32_e32 v213, v213, v212
	v_mul_f32_e32 v212, v102, v189
	v_fmac_f32_e32 v212, v101, v188
	v_fmac_f32_e32 v212, v103, v190
	v_fmac_f32_e32 v212, v104, v191
	v_add_f32_e32 v213, v213, v212
	v_mul_f32_e32 v212, v106, v193
	v_fmac_f32_e32 v212, v105, v192
	v_fmac_f32_e32 v212, v107, v194
	v_fmac_f32_e32 v212, v108, v195
	v_add_f32_e32 v213, v213, v212
	v_min_f32_e32 v214, 0, v213
	v_mul_f32_e64 v213, |v213|, s65
	v_exp_f32_e32 v213, v213
	s_nop 0
	v_add_f32_e32 v213, 1.0, v213
	v_cmp_gt_f32_e32 vcc, s88, v213
	s_nop 1
	v_cndmask_b32_e64 v212, 0, 32, vcc
	v_ldexp_f32 v213, v213, v212
	v_log_f32_e32 v213, v213
	s_nop 0
	v_mul_f32_e32 v212, 0x3f317217, v213
	v_fma_f32 v212, v213, s75, -v212
	v_fmac_f32_e32 v212, 0x3377d1cf, v213
	v_fmac_f32_e32 v212, 0x3f317217, v213
	v_cmp_lt_f32_e64 s[40:41], |v213|, s51
	s_nop 1
	v_cndmask_b32_e64 v213, v213, v212, s[40:41]
	v_cndmask_b32_e32 v212, 0, v233, vcc
	v_sub_f32_e32 v213, v213, v212
	v_sub_f32_e32 v213, v214, v213
	v_fmamk_f32 v60, v213, 0x3d800000, v59
	ds_read_b128 v[180:183], v110 offset:256
	ds_read_b128 v[184:187], v110 offset:272
	ds_read_b128 v[188:191], v110 offset:288
	ds_read_b128 v[192:195], v110 offset:304
	s_waitcnt lgkmcnt(4)
; #define LAS __attribute__((address_space(3)))
; __device__ __forceinline__ float logsigmoid_fast(float x) { return fminf(x, 0.f) - __logf(1.0f + __expf(-fabsf(x))); }
; template <int KIND, int MODE>
; __device__ __forceinline__ void scan_unit(Frame& F, int layer, int h, int vhalf, int grp) {
;     ...
;             for (int i = 0; i < RPT; ++i) { const LAS f32x4* lr = (const LAS f32x4*)(X + (tq * RPT + i) * 16); float z = bl;
; #pragma unroll
;                 for (int r = 0; r < 4; ++r) { const f32x4 l4 = lr[r]; z += l4[0] * wl[4 * r] + l4[1] * wl[4 * r + 1] + l4[2] * wl[4 * r + 2] + l4[3] * wl[4 * r + 3]; }
;                 run += logsigmoid_fast(z) * (1.0f / 16.0f); bc[i] = run; }
	v_mul_f32_e32 v212, v94, v197
	v_fmac_f32_e32 v212, v91, v196
	v_fmac_f32_e32 v212, v95, v198
	v_fmac_f32_e32 v212, v96, v199
	v_add_f32_e32 v213, v109, v212
	v_mul_f32_e32 v212, v98, v201
	v_fmac_f32_e32 v212, v97, v200
	v_fmac_f32_e32 v212, v99, v202
	v_fmac_f32_e32 v212, v100, v203
	v_add_f32_e32 v213, v213, v212
	v_mul_f32_e32 v212, v102, v205
	v_fmac_f32_e32 v212, v101, v204
	v_fmac_f32_e32 v212, v103, v206
	v_fmac_f32_e32 v212, v104, v207
	v_add_f32_e32 v213, v213, v212
	v_mul_f32_e32 v212, v106, v209
	v_fmac_f32_e32 v212, v105, v208
	v_fmac_f32_e32 v212, v107, v210
	v_fmac_f32_e32 v212, v108, v211
	v_add_f32_e32 v213, v213, v212
	v_min_f32_e32 v214, 0, v213
	v_mul_f32_e64 v213, |v213|, s65
	v_exp_f32_e32 v213, v213
	s_nop 0
	v_add_f32_e32 v213, 1.0, v213
	v_cmp_gt_f32_e32 vcc, s88, v213
	s_nop 1
	v_cndmask_b32_e64 v212, 0, 32, vcc
	v_ldexp_f32 v213, v213, v212
	v_log_f32_e32 v213, v213
	s_nop 0
	v_mul_f32_e32 v212, 0x3f317217, v213
	v_fma_f32 v212, v213, s75, -v212
	v_fmac_f32_e32 v212, 0x3377d1cf, v213
	v_fmac_f32_e32 v212, 0x3f317217, v213
	v_cmp_lt_f32_e64 s[40:41], |v213|, s51
	s_nop 1
	v_cndmask_b32_e64 v213, v213, v212, s[40:41]
	v_cndmask_b32_e32 v212, 0, v233, vcc
	v_sub_f32_e32 v213, v213, v212
	v_sub_f32_e32 v213, v214, v213
	v_fmamk_f32 v61, v213, 0x3d800000, v60
	ds_read_b128 v[196:199], v110 offset:320
	ds_read_b128 v[200:203], v110 offset:336
	ds_read_b128 v[204:207], v110 offset:352
	ds_read_b128 v[208:211], v110 offset:368
	s_waitcnt lgkmcnt(4)
	v_mul_f32_e32 v212, v94, v181
	v_fmac_f32_e32 v212, v91, v180
	v_fmac_f32_e32 v212, v95, v182
	v_fmac_f32_e32 v212, v96, v183
	v_add_f32_e32 v213, v109, v212
	v_mul_f32_e32 v212, v98, v185
	v_fmac_f32_e32 v212, v97, v184
	v_fmac_f32_e32 v212, v99, v186
	v_fmac_f32_e32 v212, v100, v187
	v_add_f32_e32 v213, v213, v212
	v_mul_f32_e32 v212, v102, v189
	v_fmac_f32_e32 v212, v101, v188
	v_fmac_f32_e32 v212, v103, v190
	v_fmac_f32_e32 v212, v104, v191
	v_add_f32_e32 v213, v213, v212
	v_mul_f32_e32 v212, v106, v193
	v_fmac_f32_e32 v212, v105, v192
	v_fmac_f32_e32 v212, v107, v194
	v_fmac_f32_e32 v212, v108, v195
	v_add_f32_e32 v213, v213, v212
	v_min_f32_e32 v214, 0, v213
	v_mul_f32_e64 v213, |v213|, s65
	v_exp_f32_e32 v213, v213
	s_nop 0
	v_add_f32_e32 v213, 1.0, v213
	v_cmp_gt_f32_e32 vcc, s88, v213
	s_nop 1
	v_cndmask_b32_e64 v212, 0, 32, vcc
	v_ldexp_f32 v213, v213, v212
	v_log_f32_e32 v213, v213
	s_nop 0
	v_mul_f32_e32 v212, 0x3f317217, v213
	v_fma_f32 v212, v213, s75, -v212
	v_fmac_f32_e32 v212, 0x3377d1cf, v213
	v_fmac_f32_e32 v212, 0x3f317217, v213
	v_cmp_lt_f32_e64 s[40:41], |v213|, s51
	s_nop 1
	v_cndmask_b32_e64 v213, v213, v212, s[40:41]
	v_cndmask_b32_e32 v212, 0, v233, vcc
	v_sub_f32_e32 v213, v213, v212
	v_sub_f32_e32 v213, v214, v213
	v_fmamk_f32 v62, v213, 0x3d800000, v61
	ds_read_b128 v[180:183], v110 offset:384
	ds_read_b128 v[184:187], v110 offset:400
	ds_read_b128 v[188:191], v110 offset:416
	ds_read_b128 v[192:195], v110 offset:432
	s_waitcnt lgkmcnt(4)
	v_mul_f32_e32 v212, v94, v197
	v_fmac_f32_e32 v212, v91, v196
	v_fmac_f32_e32 v212, v95, v198
	v_fmac_f32_e32 v212, v96, v199
	v_add_f32_e32 v213, v109, v212
	v_mul_f32_e32 v212, v98, v201
	v_fmac_f32_e32 v212, v97, v200
	v_fmac_f32_e32 v212, v99, v202
	v_fmac_f32_e32 v212, v100, v203
	v_add_f32_e32 v213, v213, v212
	v_mul_f32_e32 v212, v102, v205
	v_fmac_f32_e32 v212, v101, v204
	v_fmac_f32_e32 v212, v103, v206
	v_fmac_f32_e32 v212, v104, v207
	v_add_f32_e32 v213, v213, v212
	v_mul_f32_e32 v212, v106, v209
	v_fmac_f32_e32 v212, v105, v208
	v_fmac_f32_e32 v212, v107, v210
	v_fmac_f32_e32 v212, v108, v211
	v_add_f32_e32 v213, v213, v212
	v_min_f32_e32 v214, 0, v213
	v_mul_f32_e64 v213, |v213|, s65
	v_exp_f32_e32 v213, v213
	s_nop 0
	v_add_f32_e32 v213, 1.0, v213
	v_cmp_gt_f32_e32 vcc, s88, v213
	s_nop 1
	v_cndmask_b32_e64 v212, 0, 32, vcc
	v_ldexp_f32 v213, v213, v212
	v_log_f32_e32 v213, v213
	s_nop 0
	v_mul_f32_e32 v212, 0x3f317217, v213
	v_fma_f32 v212, v213, s75, -v212
	v_fmac_f32_e32 v212, 0x3377d1cf, v213
	v_fmac_f32_e32 v212, 0x3f317217, v213
	v_cmp_lt_f32_e64 s[40:41], |v213|, s51
	s_nop 1
	v_cndmask_b32_e64 v213, v213, v212, s[40:41]
	v_cndmask_b32_e32 v212, 0, v233, vcc
	v_sub_f32_e32 v213, v213, v212
	v_sub_f32_e32 v213, v214, v213
	v_fmamk_f32 v63, v213, 0x3d800000, v62
	ds_read_b128 v[196:199], v110 offset:448
	ds_read_b128 v[200:203], v110 offset:464
	ds_read_b128 v[204:207], v110 offset:480
	ds_read_b128 v[208:211], v110 offset:496
	s_waitcnt lgkmcnt(4)
	v_mul_f32_e32 v212, v94, v181
	v_fmac_f32_e32 v212, v91, v180
	v_fmac_f32_e32 v212, v95, v182
	v_fmac_f32_e32 v212, v96, v183
	v_add_f32_e32 v213, v109, v212
	v_mul_f32_e32 v212, v98, v185
	v_fmac_f32_e32 v212, v97, v184
	v_fmac_f32_e32 v212, v99, v186
	v_fmac_f32_e32 v212, v100, v187
	v_add_f32_e32 v213, v213, v212
	v_mul_f32_e32 v212, v102, v189
	v_fmac_f32_e32 v212, v101, v188
	v_fmac_f32_e32 v212, v103, v190
	v_fmac_f32_e32 v212, v104, v191
	v_add_f32_e32 v213, v213, v212
	v_mul_f32_e32 v212, v106, v193
	v_fmac_f32_e32 v212, v105, v192
	v_fmac_f32_e32 v212, v107, v194
	v_fmac_f32_e32 v212, v108, v195
	v_add_f32_e32 v213, v213, v212
	v_min_f32_e32 v214, 0, v213
	v_mul_f32_e64 v213, |v213|, s65
	v_exp_f32_e32 v213, v213
	s_nop 0
	v_add_f32_e32 v213, 1.0, v213
	v_cmp_gt_f32_e32 vcc, s88, v213
	s_nop 1
	v_cndmask_b32_e64 v212, 0, 32, vcc
	v_ldexp_f32 v213, v213, v212
	v_log_f32_e32 v213, v213
	s_nop 0
	v_mul_f32_e32 v212, 0x3f317217, v213
	v_fma_f32 v212, v213, s75, -v212
	v_fmac_f32_e32 v212, 0x3377d1cf, v213
	v_fmac_f32_e32 v212, 0x3f317217, v213
	v_cmp_lt_f32_e64 s[40:41], |v213|, s51
	s_nop 1
	v_cndmask_b32_e64 v213, v213, v212, s[40:41]
	v_cndmask_b32_e32 v212, 0, v233, vcc
	v_sub_f32_e32 v213, v213, v212
	v_sub_f32_e32 v213, v214, v213
	v_fmamk_f32 v65, v213, 0x3d800000, v63
	ds_read_b128 v[180:183], v110 offset:512
	ds_read_b128 v[184:187], v110 offset:528
	ds_read_b128 v[188:191], v110 offset:544
	ds_read_b128 v[192:195], v110 offset:560
	s_waitcnt lgkmcnt(4)
; #define LAS __attribute__((address_space(3)))
; __device__ __forceinline__ float logsigmoid_fast(float x) { return fminf(x, 0.f) - __logf(1.0f + __expf(-fabsf(x))); }
; template <int KIND, int MODE>
; __device__ __forceinline__ void scan_unit(Frame& F, int layer, int h, int vhalf, int grp) {
;     ...
;             for (int i = 0; i < RPT; ++i) { const LAS f32x4* lr = (const LAS f32x4*)(X + (tq * RPT + i) * 16); float z = bl;
; #pragma unroll
;                 for (int r = 0; r < 4; ++r) { const f32x4 l4 = lr[r]; z += l4[0] * wl[4 * r] + l4[1] * wl[4 * r + 1] + l4[2] * wl[4 * r + 2] + l4[3] * wl[4 * r + 3]; }
;                 run += logsigmoid_fast(z) * (1.0f / 16.0f); bc[i] = run; }
	v_mul_f32_e32 v212, v94, v197
	v_fmac_f32_e32 v212, v91, v196
	v_fmac_f32_e32 v212, v95, v198
	v_fmac_f32_e32 v212, v96, v199
	v_add_f32_e32 v213, v109, v212
	v_mul_f32_e32 v212, v98, v201
	v_fmac_f32_e32 v212, v97, v200
	v_fmac_f32_e32 v212, v99, v202
	v_fmac_f32_e32 v212, v100, v203
	v_add_f32_e32 v213, v213, v212
	v_mul_f32_e32 v212, v102, v205
	v_fmac_f32_e32 v212, v101, v204
	v_fmac_f32_e32 v212, v103, v206
	v_fmac_f32_e32 v212, v104, v207
	v_add_f32_e32 v213, v213, v212
	v_mul_f32_e32 v212, v106, v209
	v_fmac_f32_e32 v212, v105, v208
	v_fmac_f32_e32 v212, v107, v210
	v_fmac_f32_e32 v212, v108, v211
	v_add_f32_e32 v213, v213, v212
	v_min_f32_e32 v214, 0, v213
	v_mul_f32_e64 v213, |v213|, s65
	v_exp_f32_e32 v213, v213
	s_nop 0
	v_add_f32_e32 v213, 1.0, v213
	v_cmp_gt_f32_e32 vcc, s88, v213
	s_nop 1
	v_cndmask_b32_e64 v212, 0, 32, vcc
	v_ldexp_f32 v213, v213, v212
	v_log_f32_e32 v213, v213
	s_nop 0
	v_mul_f32_e32 v212, 0x3f317217, v213
	v_fma_f32 v212, v213, s75, -v212
	v_fmac_f32_e32 v212, 0x3377d1cf, v213
	v_fmac_f32_e32 v212, 0x3f317217, v213
	v_cmp_lt_f32_e64 s[40:41], |v213|, s51
	s_nop 1
	v_cndmask_b32_e64 v213, v213, v212, s[40:41]
	v_cndmask_b32_e32 v212, 0, v233, vcc
	v_sub_f32_e32 v213, v213, v212
	v_sub_f32_e32 v213, v214, v213
	v_fmamk_f32 v67, v213, 0x3d800000, v65
	ds_read_b128 v[196:199], v110 offset:576
	ds_read_b128 v[200:203], v110 offset:592
	ds_read_b128 v[204:207], v110 offset:608
	ds_read_b128 v[208:211], v110 offset:624
	s_waitcnt lgkmcnt(4)
	v_mul_f32_e32 v212, v94, v181
	v_fmac_f32_e32 v212, v91, v180
	v_fmac_f32_e32 v212, v95, v182
	v_fmac_f32_e32 v212, v96, v183
	v_add_f32_e32 v213, v109, v212
	v_mul_f32_e32 v212, v98, v185
	v_fmac_f32_e32 v212, v97, v184
	v_fmac_f32_e32 v212, v99, v186
	v_fmac_f32_e32 v212, v100, v187
	v_add_f32_e32 v213, v213, v212
	v_mul_f32_e32 v212, v102, v189
	v_fmac_f32_e32 v212, v101, v188
	v_fmac_f32_e32 v212, v103, v190
	v_fmac_f32_e32 v212, v104, v191
	v_add_f32_e32 v213, v213, v212
	v_mul_f32_e32 v212, v106, v193
	v_fmac_f32_e32 v212, v105, v192
	v_fmac_f32_e32 v212, v107, v194
	v_fmac_f32_e32 v212, v108, v195
	v_add_f32_e32 v213, v213, v212
	v_min_f32_e32 v214, 0, v213
	v_mul_f32_e64 v213, |v213|, s65
	v_exp_f32_e32 v213, v213
	s_nop 0
	v_add_f32_e32 v213, 1.0, v213
	v_cmp_gt_f32_e32 vcc, s88, v213
	s_nop 1
	v_cndmask_b32_e64 v212, 0, 32, vcc
	v_ldexp_f32 v213, v213, v212
	v_log_f32_e32 v213, v213
	s_nop 0
	v_mul_f32_e32 v212, 0x3f317217, v213
	v_fma_f32 v212, v213, s75, -v212
	v_fmac_f32_e32 v212, 0x3377d1cf, v213
	v_fmac_f32_e32 v212, 0x3f317217, v213
	v_cmp_lt_f32_e64 s[40:41], |v213|, s51
	s_nop 1
	v_cndmask_b32_e64 v213, v213, v212, s[40:41]
	v_cndmask_b32_e32 v212, 0, v233, vcc
	v_sub_f32_e32 v213, v213, v212
	v_sub_f32_e32 v213, v214, v213
	v_fmamk_f32 v64, v213, 0x3d800000, v67
	ds_read_b128 v[180:183], v110 offset:640
	ds_read_b128 v[184:187], v110 offset:656
	ds_read_b128 v[188:191], v110 offset:672
	ds_read_b128 v[192:195], v110 offset:688
	s_waitcnt lgkmcnt(4)
	v_mul_f32_e32 v212, v94, v197
	v_fmac_f32_e32 v212, v91, v196
	v_fmac_f32_e32 v212, v95, v198
	v_fmac_f32_e32 v212, v96, v199
	v_add_f32_e32 v213, v109, v212
	v_mul_f32_e32 v212, v98, v201
	v_fmac_f32_e32 v212, v97, v200
	v_fmac_f32_e32 v212, v99, v202
	v_fmac_f32_e32 v212, v100, v203
	v_add_f32_e32 v213, v213, v212
	v_mul_f32_e32 v212, v102, v205
	v_fmac_f32_e32 v212, v101, v204
	v_fmac_f32_e32 v212, v103, v206
	v_fmac_f32_e32 v212, v104, v207
	v_add_f32_e32 v213, v213, v212
	v_mul_f32_e32 v212, v106, v209
	v_fmac_f32_e32 v212, v105, v208
	v_fmac_f32_e32 v212, v107, v210
	v_fmac_f32_e32 v212, v108, v211
	v_add_f32_e32 v213, v213, v212
	v_min_f32_e32 v214, 0, v213
	v_mul_f32_e64 v213, |v213|, s65
	v_exp_f32_e32 v213, v213
	s_nop 0
	v_add_f32_e32 v213, 1.0, v213
	v_cmp_gt_f32_e32 vcc, s88, v213
	s_nop 1
	v_cndmask_b32_e64 v212, 0, 32, vcc
	v_ldexp_f32 v213, v213, v212
	v_log_f32_e32 v213, v213
	s_nop 0
	v_mul_f32_e32 v212, 0x3f317217, v213
	v_fma_f32 v212, v213, s75, -v212
	v_fmac_f32_e32 v212, 0x3377d1cf, v213
	v_fmac_f32_e32 v212, 0x3f317217, v213
	v_cmp_lt_f32_e64 s[40:41], |v213|, s51
	s_nop 1
	v_cndmask_b32_e64 v213, v213, v212, s[40:41]
	v_cndmask_b32_e32 v212, 0, v233, vcc
	v_sub_f32_e32 v213, v213, v212
	v_sub_f32_e32 v213, v214, v213
	v_fmamk_f32 v66, v213, 0x3d800000, v64
	ds_read_b128 v[196:199], v110 offset:704
	ds_read_b128 v[200:203], v110 offset:720
	ds_read_b128 v[204:207], v110 offset:736
	ds_read_b128 v[208:211], v110 offset:752
	s_waitcnt lgkmcnt(4)
	v_mul_f32_e32 v212, v94, v181
	v_fmac_f32_e32 v212, v91, v180
	v_fmac_f32_e32 v212, v95, v182
	v_fmac_f32_e32 v212, v96, v183
	v_add_f32_e32 v213, v109, v212
	v_mul_f32_e32 v212, v98, v185
	v_fmac_f32_e32 v212, v97, v184
	v_fmac_f32_e32 v212, v99, v186
	v_fmac_f32_e32 v212, v100, v187
	v_add_f32_e32 v213, v213, v212
	v_mul_f32_e32 v212, v102, v189
	v_fmac_f32_e32 v212, v101, v188
	v_fmac_f32_e32 v212, v103, v190
	v_fmac_f32_e32 v212, v104, v191
	v_add_f32_e32 v213, v213, v212
	v_mul_f32_e32 v212, v106, v193
	v_fmac_f32_e32 v212, v105, v192
	v_fmac_f32_e32 v212, v107, v194
	v_fmac_f32_e32 v212, v108, v195
	v_add_f32_e32 v213, v213, v212
	v_min_f32_e32 v214, 0, v213
	v_mul_f32_e64 v213, |v213|, s65
	v_exp_f32_e32 v213, v213
	s_nop 0
	v_add_f32_e32 v213, 1.0, v213
	v_cmp_gt_f32_e32 vcc, s88, v213
	s_nop 1
	v_cndmask_b32_e64 v212, 0, 32, vcc
	v_ldexp_f32 v213, v213, v212
	v_log_f32_e32 v213, v213
	s_nop 0
	v_mul_f32_e32 v212, 0x3f317217, v213
	v_fma_f32 v212, v213, s75, -v212
	v_fmac_f32_e32 v212, 0x3377d1cf, v213
	v_fmac_f32_e32 v212, 0x3f317217, v213
	v_cmp_lt_f32_e64 s[40:41], |v213|, s51
	s_nop 1
	v_cndmask_b32_e64 v213, v213, v212, s[40:41]
	v_cndmask_b32_e32 v212, 0, v233, vcc
	v_sub_f32_e32 v213, v213, v212
	v_sub_f32_e32 v213, v214, v213
	v_fmamk_f32 v68, v213, 0x3d800000, v66
	ds_read_b128 v[180:183], v110 offset:768
	ds_read_b128 v[184:187], v110 offset:784
	ds_read_b128 v[188:191], v110 offset:800
	ds_read_b128 v[192:195], v110 offset:816
	s_waitcnt lgkmcnt(4)
; #define LAS __attribute__((address_space(3)))
; __device__ __forceinline__ float logsigmoid_fast(float x) { return fminf(x, 0.f) - __logf(1.0f + __expf(-fabsf(x))); }
; template <int KIND, int MODE>
; __device__ __forceinline__ void scan_unit(Frame& F, int layer, int h, int vhalf, int grp) {
;     ...
;             for (int i = 0; i < RPT; ++i) { const LAS f32x4* lr = (const LAS f32x4*)(X + (tq * RPT + i) * 16); float z = bl;
; #pragma unroll
;                 for (int r = 0; r < 4; ++r) { const f32x4 l4 = lr[r]; z += l4[0] * wl[4 * r] + l4[1] * wl[4 * r + 1] + l4[2] * wl[4 * r + 2] + l4[3] * wl[4 * r + 3]; }
;                 run += logsigmoid_fast(z) * (1.0f / 16.0f); bc[i] = run; }
	v_mul_f32_e32 v212, v94, v197
	v_fmac_f32_e32 v212, v91, v196
	v_fmac_f32_e32 v212, v95, v198
	v_fmac_f32_e32 v212, v96, v199
	v_add_f32_e32 v213, v109, v212
	v_mul_f32_e32 v212, v98, v201
	v_fmac_f32_e32 v212, v97, v200
	v_fmac_f32_e32 v212, v99, v202
	v_fmac_f32_e32 v212, v100, v203
	v_add_f32_e32 v213, v213, v212
	v_mul_f32_e32 v212, v102, v205
	v_fmac_f32_e32 v212, v101, v204
	v_fmac_f32_e32 v212, v103, v206
	v_fmac_f32_e32 v212, v104, v207
	v_add_f32_e32 v213, v213, v212
	v_mul_f32_e32 v212, v106, v209
	v_fmac_f32_e32 v212, v105, v208
	v_fmac_f32_e32 v212, v107, v210
	v_fmac_f32_e32 v212, v108, v211
	v_add_f32_e32 v213, v213, v212
	v_min_f32_e32 v214, 0, v213
	v_mul_f32_e64 v213, |v213|, s65
	v_exp_f32_e32 v213, v213
	s_nop 0
	v_add_f32_e32 v213, 1.0, v213
	v_cmp_gt_f32_e32 vcc, s88, v213
	s_nop 1
	v_cndmask_b32_e64 v212, 0, 32, vcc
	v_ldexp_f32 v213, v213, v212
	v_log_f32_e32 v213, v213
	s_nop 0
	v_mul_f32_e32 v212, 0x3f317217, v213
	v_fma_f32 v212, v213, s75, -v212
	v_fmac_f32_e32 v212, 0x3377d1cf, v213
	v_fmac_f32_e32 v212, 0x3f317217, v213
	v_cmp_lt_f32_e64 s[40:41], |v213|, s51
	s_nop 1
	v_cndmask_b32_e64 v213, v213, v212, s[40:41]
	v_cndmask_b32_e32 v212, 0, v233, vcc
	v_sub_f32_e32 v213, v213, v212
	v_sub_f32_e32 v213, v214, v213
	v_fmamk_f32 v69, v213, 0x3d800000, v68
	ds_read_b128 v[196:199], v110 offset:832
	ds_read_b128 v[200:203], v110 offset:848
	ds_read_b128 v[204:207], v110 offset:864
	ds_read_b128 v[208:211], v110 offset:880
	s_waitcnt lgkmcnt(4)
	v_mul_f32_e32 v212, v94, v181
	v_fmac_f32_e32 v212, v91, v180
	v_fmac_f32_e32 v212, v95, v182
	v_fmac_f32_e32 v212, v96, v183
	v_add_f32_e32 v213, v109, v212
	v_mul_f32_e32 v212, v98, v185
	v_fmac_f32_e32 v212, v97, v184
	v_fmac_f32_e32 v212, v99, v186
	v_fmac_f32_e32 v212, v100, v187
	v_add_f32_e32 v213, v213, v212
	v_mul_f32_e32 v212, v102, v189
	v_fmac_f32_e32 v212, v101, v188
	v_fmac_f32_e32 v212, v103, v190
	v_fmac_f32_e32 v212, v104, v191
	v_add_f32_e32 v213, v213, v212
	v_mul_f32_e32 v212, v106, v193
	v_fmac_f32_e32 v212, v105, v192
	v_fmac_f32_e32 v212, v107, v194
	v_fmac_f32_e32 v212, v108, v195
	v_add_f32_e32 v213, v213, v212
	v_min_f32_e32 v214, 0, v213
	v_mul_f32_e64 v213, |v213|, s65
	v_exp_f32_e32 v213, v213
	s_nop 0
	v_add_f32_e32 v213, 1.0, v213
	v_cmp_gt_f32_e32 vcc, s88, v213
	s_nop 1
	v_cndmask_b32_e64 v212, 0, 32, vcc
	v_ldexp_f32 v213, v213, v212
	v_log_f32_e32 v213, v213
	s_nop 0
	v_mul_f32_e32 v212, 0x3f317217, v213
	v_fma_f32 v212, v213, s75, -v212
	v_fmac_f32_e32 v212, 0x3377d1cf, v213
	v_fmac_f32_e32 v212, 0x3f317217, v213
	v_cmp_lt_f32_e64 s[40:41], |v213|, s51
	s_nop 1
	v_cndmask_b32_e64 v213, v213, v212, s[40:41]
	v_cndmask_b32_e32 v212, 0, v233, vcc
	v_sub_f32_e32 v213, v213, v212
	v_sub_f32_e32 v213, v214, v213
	v_fmamk_f32 v70, v213, 0x3d800000, v69
	ds_read_b128 v[180:183], v110 offset:896
	ds_read_b128 v[184:187], v110 offset:912
	ds_read_b128 v[188:191], v110 offset:928
	ds_read_b128 v[192:195], v110 offset:944
	s_waitcnt lgkmcnt(4)
	v_mul_f32_e32 v212, v94, v197
	v_fmac_f32_e32 v212, v91, v196
	v_fmac_f32_e32 v212, v95, v198
	v_fmac_f32_e32 v212, v96, v199
	v_add_f32_e32 v213, v109, v212
	v_mul_f32_e32 v212, v98, v201
	v_fmac_f32_e32 v212, v97, v200
	v_fmac_f32_e32 v212, v99, v202
	v_fmac_f32_e32 v212, v100, v203
	v_add_f32_e32 v213, v213, v212
	v_mul_f32_e32 v212, v102, v205
	v_fmac_f32_e32 v212, v101, v204
	v_fmac_f32_e32 v212, v103, v206
	v_fmac_f32_e32 v212, v104, v207
	v_add_f32_e32 v213, v213, v212
	v_mul_f32_e32 v212, v106, v209
	v_fmac_f32_e32 v212, v105, v208
	v_fmac_f32_e32 v212, v107, v210
	v_fmac_f32_e32 v212, v108, v211
	v_add_f32_e32 v213, v213, v212
	v_min_f32_e32 v214, 0, v213
	v_mul_f32_e64 v213, |v213|, s65
	v_exp_f32_e32 v213, v213
	s_nop 0
	v_add_f32_e32 v213, 1.0, v213
	v_cmp_gt_f32_e32 vcc, s88, v213
	s_nop 1
	v_cndmask_b32_e64 v212, 0, 32, vcc
	v_ldexp_f32 v213, v213, v212
	v_log_f32_e32 v213, v213
	s_nop 0
	v_mul_f32_e32 v212, 0x3f317217, v213
	v_fma_f32 v212, v213, s75, -v212
	v_fmac_f32_e32 v212, 0x3377d1cf, v213
	v_fmac_f32_e32 v212, 0x3f317217, v213
	v_cmp_lt_f32_e64 s[40:41], |v213|, s51
	s_nop 1
	v_cndmask_b32_e64 v213, v213, v212, s[40:41]
	v_cndmask_b32_e32 v212, 0, v233, vcc
	v_sub_f32_e32 v213, v213, v212
	v_sub_f32_e32 v213, v214, v213
	v_fmamk_f32 v72, v213, 0x3d800000, v70
	ds_read_b128 v[196:199], v110 offset:960
	ds_read_b128 v[200:203], v110 offset:976
	ds_read_b128 v[204:207], v110 offset:992
	ds_read_b128 v[208:211], v110 offset:1008
	s_waitcnt lgkmcnt(4)
	v_mul_f32_e32 v212, v94, v181
	v_fmac_f32_e32 v212, v91, v180
	v_fmac_f32_e32 v212, v95, v182
	v_fmac_f32_e32 v212, v96, v183
	v_add_f32_e32 v213, v109, v212
	v_mul_f32_e32 v212, v98, v185
	v_fmac_f32_e32 v212, v97, v184
	v_fmac_f32_e32 v212, v99, v186
	v_fmac_f32_e32 v212, v100, v187
	v_add_f32_e32 v213, v213, v212
	v_mul_f32_e32 v212, v102, v189
	v_fmac_f32_e32 v212, v101, v188
	v_fmac_f32_e32 v212, v103, v190
	v_fmac_f32_e32 v212, v104, v191
	v_add_f32_e32 v213, v213, v212
	v_mul_f32_e32 v212, v106, v193
	v_fmac_f32_e32 v212, v105, v192
	v_fmac_f32_e32 v212, v107, v194
	v_fmac_f32_e32 v212, v108, v195
	v_add_f32_e32 v213, v213, v212
	v_min_f32_e32 v214, 0, v213
	v_mul_f32_e64 v213, |v213|, s65
	v_exp_f32_e32 v213, v213
	s_nop 0
	v_add_f32_e32 v213, 1.0, v213
	v_cmp_gt_f32_e32 vcc, s88, v213
	s_nop 1
	v_cndmask_b32_e64 v212, 0, 32, vcc
	v_ldexp_f32 v213, v213, v212
	v_log_f32_e32 v213, v213
	s_nop 0
	v_mul_f32_e32 v212, 0x3f317217, v213
	v_fma_f32 v212, v213, s75, -v212
	v_fmac_f32_e32 v212, 0x3377d1cf, v213
	v_fmac_f32_e32 v212, 0x3f317217, v213
	v_cmp_lt_f32_e64 s[40:41], |v213|, s51
	s_nop 1
	v_cndmask_b32_e64 v213, v213, v212, s[40:41]
	v_cndmask_b32_e32 v212, 0, v233, vcc
	v_sub_f32_e32 v213, v213, v212
	v_sub_f32_e32 v213, v214, v213
	v_fmamk_f32 v73, v213, 0x3d800000, v72
	s_waitcnt lgkmcnt(0)
; #define LAS __attribute__((address_space(3)))
; __device__ __forceinline__ unsigned pk2hw(float lo, float hi) { unsigned r; asm("s_nop 1\n\tv_cvt_pk_bf16_f32 %0, %1, %2" : "=v"(r) : "v"(lo), "v"(hi)); return r; }
; __device__ __forceinline__ float logsigmoid_fast(float x) { return fminf(x, 0.f) - __logf(1.0f + __expf(-fabsf(x))); }
; template <int KIND, int MODE>
; __device__ __forceinline__ void scan_unit(Frame& F, int layer, int h, int vhalf, int grp) {
;     ...
;             for (int i = 0; i < RPT; ++i) { const LAS f32x4* lr = (const LAS f32x4*)(X + (tq * RPT + i) * 16); float z = bl;
; #pragma unroll
;                 for (int r = 0; r < 4; ++r) { const f32x4 l4 = lr[r]; z += l4[0] * wl[4 * r] + l4[1] * wl[4 * r + 1] + l4[2] * wl[4 * r + 2] + l4[3] * wl[4 * r + 3]; }
;                 run += logsigmoid_fast(z) * (1.0f / 16.0f); bc[i] = run; }
;             X[1024 + tq * 128 + d] = run;
;             __syncthreads();
;             float pre = 0.f, tot = 0.f;
; #pragma unroll
;             for (int qq = 0; qq < NTQ; ++qq) { const float v = X[1024 + qq * 128 + d]; tot += v; if (qq < tq) pre += v; }
;             const float etot = __expf(tot);
;             if (tq == 0) { X[1536 + d] = etot; gtot += tot; }
; #pragma unroll
;             for (int i = 0; i < RPT; ++i) { const int t = tq * RPT + i; const float bcv = bc[i] + pre;
;                 const float kv = bf2f(KS[t * QST + d]); const float eb = __expf(bcv), ib = __builtin_amdgcn_rcpf(eb);
;                 if (MODE == 1) { const float qv = bf2f(QS[t * QST + d]); const unsigned w0 = pk2hw(qv * 0.08838834764831845f * eb, kv * ib); QS[t * QST + d] = (unsigned short)w0; KS[t * QST + d] = (unsigned short)(w0 >> 16); }
;                 K2[t * QST + d] = (unsigned short)pk2hw(kv * (etot * ib), 0.f); }
	v_mul_f32_e32 v212, v94, v197
	v_fmac_f32_e32 v212, v91, v196
	v_fmac_f32_e32 v212, v95, v198
	v_fmac_f32_e32 v212, v96, v199
	v_add_f32_e32 v213, v109, v212
	v_mul_f32_e32 v212, v98, v201
	v_fmac_f32_e32 v212, v97, v200
	v_fmac_f32_e32 v212, v99, v202
	v_fmac_f32_e32 v212, v100, v203
	v_add_f32_e32 v213, v213, v212
	v_mul_f32_e32 v212, v102, v205
	v_fmac_f32_e32 v212, v101, v204
	v_fmac_f32_e32 v212, v103, v206
	v_fmac_f32_e32 v212, v104, v207
	v_add_f32_e32 v213, v213, v212
	v_mul_f32_e32 v212, v106, v209
	v_fmac_f32_e32 v212, v105, v208
	v_fmac_f32_e32 v212, v107, v210
	v_fmac_f32_e32 v212, v108, v211
	v_add_f32_e32 v213, v213, v212
	v_min_f32_e32 v214, 0, v213
	v_mul_f32_e64 v213, |v213|, s65
	v_exp_f32_e32 v213, v213
	s_nop 0
	v_add_f32_e32 v213, 1.0, v213
	v_cmp_gt_f32_e32 vcc, s88, v213
	s_nop 1
	v_cndmask_b32_e64 v212, 0, 32, vcc
	v_ldexp_f32 v213, v213, v212
	v_log_f32_e32 v213, v213
	s_nop 0
	v_mul_f32_e32 v212, 0x3f317217, v213
	v_fma_f32 v212, v213, s75, -v212
	v_fmac_f32_e32 v212, 0x3377d1cf, v213
	v_fmac_f32_e32 v212, 0x3f317217, v213
	v_cmp_lt_f32_e64 s[40:41], |v213|, s51
	s_nop 1
	v_cndmask_b32_e64 v213, v213, v212, s[40:41]
	v_cndmask_b32_e32 v212, 0, v233, vcc
	v_sub_f32_e32 v213, v213, v212
	v_sub_f32_e32 v213, v214, v213
	v_fmamk_f32 v74, v213, 0x3d800000, v73
	ds_write_b32 v114, v74 offset:4096
	s_waitcnt lgkmcnt(0)
	s_barrier
	ds_read_b32 v71, v121
	ds_read_b32 v76, v122
	ds_read_b32 v77, v123
	ds_read_b32 v78, v124
	s_waitcnt lgkmcnt(0)
	v_add_f32_e32 v75, 0, v71
	s_waitcnt lgkmcnt(2)
	v_add_f32_e32 v71, v75, v76
	s_waitcnt lgkmcnt(1)
	v_add_f32_e32 v71, v71, v77
	s_waitcnt lgkmcnt(0)
	v_add_f32_e32 v71, v71, v78
	v_mul_f32_e32 v71, 0x3fb8aa3b, v71
	v_exp_f32_e32 v71, v71
	s_and_saveexec_b64 s[0:1], s[8:9]
	ds_write_b32 v112, v71 offset:6144
	s_or_b64 exec, exec, s[0:1]
	v_cndmask_b32_e64 v75, 0, v75, s[14:15]
	v_add_f32_e32 v76, v76, v75
	v_cndmask_b32_e64 v75, v75, v76, s[16:17]
	v_add_f32_e32 v76, v77, v75
	v_cndmask_b32_e64 v75, v75, v76, s[18:19]
	v_add_f32_e32 v76, v78, v75
	v_cndmask_b32_e64 v75, v75, v76, s[20:21]
	v_add_f32_e32 v58, v58, v75
	v_mul_f32_e32 v58, 0x3fb8aa3b, v58
	ds_read_u16 v76, v125 offset:33792
	ds_read_u16 v78, v125
	v_exp_f32_e32 v58, v58
	s_cmp_ge_i32 s54, s53
	s_waitcnt lgkmcnt(0)
	v_lshlrev_b32_e32 v76, 16, v76
	v_rcp_f32_e32 v77, v58
	s_waitcnt lgkmcnt(0)
	v_lshlrev_b32_e32 v78, 16, v78
	v_mul_f32_e32 v78, 0x3db504f3, v78
	v_mul_f32_e32 v58, v58, v78
	v_mul_f32_e32 v78, v77, v76
	s_nop 1
	v_cvt_pk_bf16_f32 v58, v58, v78
	ds_write_b16 v125, v58
	ds_write_b16_d16_hi v125, v58 offset:33792
	v_mul_f32_e32 v58, v71, v77
	v_mul_f32_e32 v58, v58, v76
	s_nop 1
	v_cvt_pk_bf16_f32 v58, v58, v1
	ds_write_b16 v126, v58
	v_add_f32_e32 v58, v59, v75
	v_mul_f32_e32 v58, 0x3fb8aa3b, v58
	ds_read_u16 v59, v125 offset:34064
	ds_read_u16 v77, v125 offset:272
	v_exp_f32_e32 v58, v58
	s_waitcnt lgkmcnt(0)
	v_lshlrev_b32_e32 v59, 16, v59
	v_rcp_f32_e32 v76, v58
	s_waitcnt lgkmcnt(0)
	v_lshlrev_b32_e32 v77, 16, v77
	v_mul_f32_e32 v77, 0x3db504f3, v77
	v_mul_f32_e32 v58, v58, v77
	v_mul_f32_e32 v77, v76, v59
	s_nop 1
	v_cvt_pk_bf16_f32 v58, v58, v77
	ds_write_b16 v125, v58 offset:272
	ds_write_b16_d16_hi v125, v58 offset:34064
	v_mul_f32_e32 v58, v71, v76
	v_mul_f32_e32 v58, v58, v59
	s_nop 1
	v_cvt_pk_bf16_f32 v58, v58, v1
	ds_write_b16 v127, v58
	v_add_f32_e32 v58, v60, v75
	v_mul_f32_e32 v58, 0x3fb8aa3b, v58
	ds_read_u16 v59, v125 offset:34336
	ds_read_u16 v76, v125 offset:544
	v_exp_f32_e32 v58, v58
	s_waitcnt lgkmcnt(0)
	v_lshlrev_b32_e32 v59, 16, v59
	v_rcp_f32_e32 v60, v58
	s_waitcnt lgkmcnt(0)
	v_lshlrev_b32_e32 v76, 16, v76
	v_mul_f32_e32 v76, 0x3db504f3, v76
	v_mul_f32_e32 v58, v58, v76
	v_mul_f32_e32 v76, v60, v59
	s_nop 1
	v_cvt_pk_bf16_f32 v58, v58, v76
	ds_write_b16 v125, v58 offset:544
	ds_write_b16_d16_hi v125, v58 offset:34336
	v_mul_f32_e32 v58, v71, v60
	v_mul_f32_e32 v58, v58, v59
	s_nop 1
	v_cvt_pk_bf16_f32 v58, v58, v1
	ds_write_b16 v128, v58
	v_add_f32_e32 v58, v61, v75
	v_mul_f32_e32 v58, 0x3fb8aa3b, v58
	ds_read_u16 v59, v125 offset:34608
	ds_read_u16 v61, v125 offset:816
	v_exp_f32_e32 v58, v58
	s_waitcnt lgkmcnt(0)
	v_lshlrev_b32_e32 v59, 16, v59
	v_rcp_f32_e32 v60, v58
	s_waitcnt lgkmcnt(0)
	v_lshlrev_b32_e32 v61, 16, v61
	v_mul_f32_e32 v61, 0x3db504f3, v61
	v_mul_f32_e32 v58, v58, v61
	v_mul_f32_e32 v61, v60, v59
	s_nop 1
	v_cvt_pk_bf16_f32 v58, v58, v61
	ds_write_b16 v125, v58 offset:816
	ds_write_b16_d16_hi v125, v58 offset:34608
	v_mul_f32_e32 v58, v71, v60
	v_mul_f32_e32 v58, v58, v59
	s_nop 1
	v_cvt_pk_bf16_f32 v58, v58, v1
	ds_write_b16 v129, v58
	v_add_f32_e32 v58, v62, v75
	v_mul_f32_e32 v58, 0x3fb8aa3b, v58
	ds_read_u16 v59, v125 offset:34880
	ds_read_u16 v61, v125 offset:1088
	v_exp_f32_e32 v58, v58
	s_waitcnt lgkmcnt(0)
	v_lshlrev_b32_e32 v59, 16, v59
	v_rcp_f32_e32 v60, v58
	s_waitcnt lgkmcnt(0)
	v_lshlrev_b32_e32 v61, 16, v61
	v_mul_f32_e32 v61, 0x3db504f3, v61
	v_mul_f32_e32 v58, v58, v61
	v_mul_f32_e32 v61, v60, v59
	s_nop 1
	v_cvt_pk_bf16_f32 v58, v58, v61
	ds_write_b16 v125, v58 offset:1088
	ds_write_b16_d16_hi v125, v58 offset:34880
	v_mul_f32_e32 v58, v71, v60
	v_mul_f32_e32 v58, v58, v59
	s_nop 1
	v_cvt_pk_bf16_f32 v58, v58, v1
	ds_write_b16 v130, v58
	v_add_f32_e32 v58, v63, v75
	v_mul_f32_e32 v58, 0x3fb8aa3b, v58
	ds_read_u16 v59, v125 offset:35152
	ds_read_u16 v61, v125 offset:1360
	v_exp_f32_e32 v58, v58
	s_waitcnt lgkmcnt(0)
	v_lshlrev_b32_e32 v59, 16, v59
	v_rcp_f32_e32 v60, v58
	s_waitcnt lgkmcnt(0)
; __device__ __forceinline__ unsigned pk2hw(float lo, float hi) { unsigned r; asm("s_nop 1\n\tv_cvt_pk_bf16_f32 %0, %1, %2" : "=v"(r) : "v"(lo), "v"(hi)); return r; }
; template <int KIND, int MODE>
; __device__ __forceinline__ void scan_unit(Frame& F, int layer, int h, int vhalf, int grp) {
;     ...
;             for (int i = 0; i < RPT; ++i) { const int t = tq * RPT + i; const float bcv = bc[i] + pre;
;                 const float kv = bf2f(KS[t * QST + d]); const float eb = __expf(bcv), ib = __builtin_amdgcn_rcpf(eb);
;                 if (MODE == 1) { const float qv = bf2f(QS[t * QST + d]); const unsigned w0 = pk2hw(qv * 0.08838834764831845f * eb, kv * ib); QS[t * QST + d] = (unsigned short)w0; KS[t * QST + d] = (unsigned short)(w0 >> 16); }
;                 K2[t * QST + d] = (unsigned short)pk2hw(kv * (etot * ib), 0.f); }
;             if (PREF && ch + 1 < (grp + 1) * GC) SCAN_LOAD(tb + 64);
	v_lshlrev_b32_e32 v61, 16, v61
	v_mul_f32_e32 v61, 0x3db504f3, v61
	v_mul_f32_e32 v58, v58, v61
	v_mul_f32_e32 v61, v60, v59
	s_nop 1
	v_cvt_pk_bf16_f32 v58, v58, v61
	ds_write_b16 v125, v58 offset:1360
	ds_write_b16_d16_hi v125, v58 offset:35152
	v_mul_f32_e32 v58, v71, v60
	v_mul_f32_e32 v58, v58, v59
	s_nop 1
	v_cvt_pk_bf16_f32 v58, v58, v1
	ds_write_b16 v131, v58
	v_add_f32_e32 v58, v65, v75
	v_mul_f32_e32 v58, 0x3fb8aa3b, v58
	ds_read_u16 v59, v125 offset:35424
	ds_read_u16 v61, v125 offset:1632
	v_exp_f32_e32 v58, v58
	s_waitcnt lgkmcnt(0)
	v_lshlrev_b32_e32 v59, 16, v59
	v_rcp_f32_e32 v60, v58
	s_waitcnt lgkmcnt(0)
	v_lshlrev_b32_e32 v61, 16, v61
	v_mul_f32_e32 v61, 0x3db504f3, v61
	v_mul_f32_e32 v58, v58, v61
	v_mul_f32_e32 v61, v60, v59
	s_nop 1
	v_cvt_pk_bf16_f32 v58, v58, v61
	ds_write_b16 v125, v58 offset:1632
	ds_write_b16_d16_hi v125, v58 offset:35424
	v_mul_f32_e32 v58, v71, v60
	v_mul_f32_e32 v58, v58, v59
	s_nop 1
	v_cvt_pk_bf16_f32 v58, v58, v1
	ds_write_b16 v132, v58
	v_add_f32_e32 v58, v67, v75
	v_mul_f32_e32 v58, 0x3fb8aa3b, v58
	ds_read_u16 v59, v125 offset:35696
	ds_read_u16 v61, v125 offset:1904
	v_exp_f32_e32 v58, v58
	s_waitcnt lgkmcnt(0)
	v_lshlrev_b32_e32 v59, 16, v59
	v_rcp_f32_e32 v60, v58
	s_waitcnt lgkmcnt(0)
	v_lshlrev_b32_e32 v61, 16, v61
	v_mul_f32_e32 v61, 0x3db504f3, v61
	v_mul_f32_e32 v58, v58, v61
	v_mul_f32_e32 v61, v60, v59
	s_nop 1
	v_cvt_pk_bf16_f32 v58, v58, v61
	ds_write_b16 v125, v58 offset:1904
	ds_write_b16_d16_hi v125, v58 offset:35696
	v_mul_f32_e32 v58, v71, v60
	v_mul_f32_e32 v58, v58, v59
	s_nop 1
	v_cvt_pk_bf16_f32 v58, v58, v1
	ds_write_b16 v133, v58
	v_add_f32_e32 v58, v64, v75
	v_mul_f32_e32 v58, 0x3fb8aa3b, v58
	ds_read_u16 v59, v125 offset:35968
	ds_read_u16 v61, v125 offset:2176
	v_exp_f32_e32 v58, v58
	s_waitcnt lgkmcnt(0)
	v_lshlrev_b32_e32 v59, 16, v59
	v_rcp_f32_e32 v60, v58
	s_waitcnt lgkmcnt(0)
	v_lshlrev_b32_e32 v61, 16, v61
	v_mul_f32_e32 v61, 0x3db504f3, v61
	v_mul_f32_e32 v58, v58, v61
	v_mul_f32_e32 v61, v60, v59
	s_nop 1
	v_cvt_pk_bf16_f32 v58, v58, v61
	ds_write_b16 v125, v58 offset:2176
	ds_write_b16_d16_hi v125, v58 offset:35968
	v_mul_f32_e32 v58, v71, v60
	v_mul_f32_e32 v58, v58, v59
	s_nop 1
	v_cvt_pk_bf16_f32 v58, v58, v1
	ds_write_b16 v134, v58
	v_add_f32_e32 v58, v66, v75
	v_mul_f32_e32 v58, 0x3fb8aa3b, v58
	ds_read_u16 v59, v125 offset:36240
	ds_read_u16 v61, v125 offset:2448
	v_exp_f32_e32 v58, v58
	s_waitcnt lgkmcnt(0)
	v_lshlrev_b32_e32 v59, 16, v59
	v_rcp_f32_e32 v60, v58
	s_waitcnt lgkmcnt(0)
	v_lshlrev_b32_e32 v61, 16, v61
	v_mul_f32_e32 v61, 0x3db504f3, v61
	v_mul_f32_e32 v58, v58, v61
	v_mul_f32_e32 v61, v60, v59
	s_nop 1
	v_cvt_pk_bf16_f32 v58, v58, v61
	ds_write_b16 v125, v58 offset:2448
	ds_write_b16_d16_hi v125, v58 offset:36240
	v_mul_f32_e32 v58, v71, v60
	v_mul_f32_e32 v58, v58, v59
	s_nop 1
	v_cvt_pk_bf16_f32 v58, v58, v1
	ds_write_b16 v135, v58
	v_add_f32_e32 v58, v68, v75
	v_mul_f32_e32 v58, 0x3fb8aa3b, v58
	ds_read_u16 v59, v125 offset:36512
	ds_read_u16 v61, v125 offset:2720
	v_exp_f32_e32 v58, v58
	s_waitcnt lgkmcnt(0)
	v_lshlrev_b32_e32 v59, 16, v59
	v_rcp_f32_e32 v60, v58
	s_waitcnt lgkmcnt(0)
	v_lshlrev_b32_e32 v61, 16, v61
	v_mul_f32_e32 v61, 0x3db504f3, v61
	v_mul_f32_e32 v58, v58, v61
	v_mul_f32_e32 v61, v60, v59
	s_nop 1
	v_cvt_pk_bf16_f32 v58, v58, v61
	ds_write_b16 v125, v58 offset:2720
	ds_write_b16_d16_hi v125, v58 offset:36512
	v_mul_f32_e32 v58, v71, v60
	v_mul_f32_e32 v58, v58, v59
	s_nop 1
	v_cvt_pk_bf16_f32 v58, v58, v1
	ds_write_b16 v136, v58
	v_add_f32_e32 v58, v69, v75
	v_mul_f32_e32 v58, 0x3fb8aa3b, v58
	ds_read_u16 v59, v125 offset:36784
	ds_read_u16 v61, v125 offset:2992
	v_exp_f32_e32 v58, v58
	s_waitcnt lgkmcnt(0)
	v_lshlrev_b32_e32 v59, 16, v59
	v_rcp_f32_e32 v60, v58
	s_waitcnt lgkmcnt(0)
	v_lshlrev_b32_e32 v61, 16, v61
	v_mul_f32_e32 v61, 0x3db504f3, v61
	v_mul_f32_e32 v58, v58, v61
	v_mul_f32_e32 v61, v60, v59
	s_nop 1
	v_cvt_pk_bf16_f32 v58, v58, v61
	ds_write_b16 v125, v58 offset:2992
	ds_write_b16_d16_hi v125, v58 offset:36784
	v_mul_f32_e32 v58, v71, v60
	v_mul_f32_e32 v58, v58, v59
	s_nop 1
	v_cvt_pk_bf16_f32 v58, v58, v1
	ds_write_b16 v137, v58
	v_add_f32_e32 v58, v70, v75
	v_mul_f32_e32 v58, 0x3fb8aa3b, v58
	ds_read_u16 v59, v125 offset:37056
	ds_read_u16 v61, v125 offset:3264
	v_exp_f32_e32 v58, v58
	s_waitcnt lgkmcnt(0)
	v_lshlrev_b32_e32 v59, 16, v59
	v_rcp_f32_e32 v60, v58
	s_waitcnt lgkmcnt(0)
	v_lshlrev_b32_e32 v61, 16, v61
	v_mul_f32_e32 v61, 0x3db504f3, v61
	v_mul_f32_e32 v58, v58, v61
	v_mul_f32_e32 v61, v60, v59
	s_nop 1
	v_cvt_pk_bf16_f32 v58, v58, v61
	ds_write_b16 v125, v58 offset:3264
	ds_write_b16_d16_hi v125, v58 offset:37056
	v_mul_f32_e32 v58, v71, v60
	v_mul_f32_e32 v58, v58, v59
	s_nop 1
	v_cvt_pk_bf16_f32 v58, v58, v1
	ds_write_b16 v138, v58
	v_add_f32_e32 v58, v72, v75
	v_mul_f32_e32 v58, 0x3fb8aa3b, v58
	ds_read_u16 v59, v125 offset:37328
	ds_read_u16 v61, v125 offset:3536
	v_exp_f32_e32 v58, v58
	s_waitcnt lgkmcnt(0)
	v_lshlrev_b32_e32 v59, 16, v59
	v_rcp_f32_e32 v60, v58
	s_waitcnt lgkmcnt(0)
	v_lshlrev_b32_e32 v61, 16, v61
	v_mul_f32_e32 v61, 0x3db504f3, v61
	v_mul_f32_e32 v58, v58, v61
	v_mul_f32_e32 v61, v60, v59
	s_nop 1
	v_cvt_pk_bf16_f32 v58, v58, v61
	ds_write_b16 v125, v58 offset:3536
	ds_write_b16_d16_hi v125, v58 offset:37328
	v_mul_f32_e32 v58, v71, v60
	v_mul_f32_e32 v58, v58, v59
	s_nop 1
	v_cvt_pk_bf16_f32 v58, v58, v1
	ds_write_b16 v139, v58
	v_add_f32_e32 v58, v73, v75
	v_mul_f32_e32 v58, 0x3fb8aa3b, v58
	ds_read_u16 v59, v125 offset:37600
	ds_read_u16 v61, v125 offset:3808
	v_exp_f32_e32 v58, v58
	s_waitcnt lgkmcnt(0)
	v_lshlrev_b32_e32 v59, 16, v59
	v_rcp_f32_e32 v60, v58
	s_waitcnt lgkmcnt(0)
	v_lshlrev_b32_e32 v61, 16, v61
	v_mul_f32_e32 v61, 0x3db504f3, v61
	v_mul_f32_e32 v58, v58, v61
	v_mul_f32_e32 v61, v60, v59
	s_nop 1
	v_cvt_pk_bf16_f32 v58, v58, v61
	ds_write_b16 v125, v58 offset:3808
	ds_write_b16_d16_hi v125, v58 offset:37600
	v_mul_f32_e32 v58, v71, v60
	v_mul_f32_e32 v58, v58, v59
	s_nop 1
	v_cvt_pk_bf16_f32 v58, v58, v1
	ds_write_b16 v140, v58
	v_add_f32_e32 v58, v75, v74
	v_mul_f32_e32 v58, 0x3fb8aa3b, v58
	ds_read_u16 v59, v125 offset:37872
	ds_read_u16 v61, v125 offset:4080
	v_exp_f32_e32 v58, v58
	s_waitcnt lgkmcnt(0)
	v_lshlrev_b32_e32 v59, 16, v59
	v_rcp_f32_e32 v60, v58
	s_waitcnt lgkmcnt(0)
	v_lshlrev_b32_e32 v61, 16, v61
	v_mul_f32_e32 v61, 0x3db504f3, v61
	v_mul_f32_e32 v58, v58, v61
	v_mul_f32_e32 v61, v60, v59
	s_nop 1
	v_cvt_pk_bf16_f32 v58, v58, v61
	ds_write_b16 v125, v58 offset:4080
	ds_write_b16_d16_hi v125, v58 offset:37872
	v_mul_f32_e32 v58, v71, v60
	v_mul_f32_e32 v58, v58, v59
	s_nop 1
	v_cvt_pk_bf16_f32 v58, v58, v1
	ds_write_b16 v141, v58
	s_cbranch_scc1 .LBB0_562
	v_add_u32_e32 v56, s52, v148
	v_add_u32_e32 v54, 64, v56
	v_mov_b64_e32 v[52:53], s[60:61]
	v_add_u32_e32 v56, 0x60, v56
	v_mad_i64_i32 v[34:35], s[0:1], v54, s59, v[84:85]
	v_mad_i64_i32 v[50:51], s[0:1], v54, s59, v[86:87]
	v_mad_i64_i32 v[54:55], s[0:1], v54, s59, v[52:53]
	v_mad_i64_i32 v[52:53], s[0:1], v56, s59, v[52:53]
	v_lshl_add_u64 v[52:53], v[52:53], 0, v[0:1]
	v_add_co_u32_e32 v52, vcc, 0x6000, v52
	v_add_u32_e32 v42, s52, v149
	v_lshl_add_u64 v[54:55], v[54:55], 0, v[0:1]
	v_addc_co_u32_e32 v53, vcc, 0, v53, vcc
	v_mad_i64_i32 v[38:39], s[0:1], v42, s59, v[84:85]
	v_mad_i64_i32 v[42:43], s[0:1], v42, s59, v[86:87]
	v_add_co_u32_e32 v54, vcc, 0x6000, v54
	flat_load_dwordx4 v[34:37], v[34:35]
	s_nop 0
	flat_load_dwordx4 v[38:41], v[38:39]
	s_nop 0
	flat_load_dwordx4 v[46:49], v[42:43] offset:1024
	s_nop 0
	flat_load_dwordx4 v[42:45], v[42:43]
	v_addc_co_u32_e32 v55, vcc, 0, v55, vcc
	flat_load_ushort v58, v[52:53]
	flat_load_ushort v59, v[54:55]
	s_nop 0
	flat_load_dwordx4 v[54:57], v[50:51] offset:1024
	s_nop 0
	flat_load_dwordx4 v[50:53], v[50:51]
	s_waitcnt vmcnt(0) lgkmcnt(0)
	v_lshlrev_b32_e32 v90, 16, v58
	v_lshlrev_b32_e32 v89, 16, v59
